# v16 + attention phases: 225 packed fp32 VALU ops (v_pk_mul/add/fma_f32) split into scalar pairs, bit-identical
# speedup vs baseline: 1.0059x; 1.0025x over previous
.LBB0_1098:
	v_div_scale_f32 v0, s[8:9], v35, v35, 1.0
	v_rcp_f32_e32 v34, v0
	v_div_scale_f32 v36, vcc, 1.0, v35, 1.0
	s_lshl_b32 s12, s66, 1
	v_fma_f32 v37, -v0, v34, 1.0
	v_fmac_f32_e32 v34, v37, v34
	v_mul_f32_e32 v37, v36, v34
	v_fma_f32 v38, -v0, v37, v36
	v_fmac_f32_e32 v37, v38, v34
	v_fma_f32 v0, -v0, v37, v36
	v_div_fmas_f32 v0, v0, v34, v37
	v_div_fixup_f32 v0, v0, v35, 1.0
	v_lshlrev_b64 v[34:35], 12, v[98:99]
	v_lshl_add_u64 v[34:35], s[62:63], 0, v[34:35]
	v_mul_f32_e32 v4, v4, v0
	v_mul_f32_e32 v5, v5, v0
	v_mul_f32_e32 v2, v2, v0
	v_mul_f32_e32 v3, v3, v0
	v_lshl_add_u64 v[34:35], v[34:35], 0, s[12:13]
	v_ashrrev_i32_e32 v101, 31, v100
	v_mul_f32_e32 v8, v8, v0
	v_mul_f32_e32 v9, v9, v0
	v_mul_f32_e32 v6, v6, v0
	v_mul_f32_e32 v7, v7, v0
	v_lshl_add_u64 v[34:35], v[100:101], 1, v[34:35]
	v_cvt_pk_bf16_f32 v2, v2, v3
	v_cvt_pk_bf16_f32 v3, v4, v5
	v_mul_f32_e32 v12, v12, v0
	v_mul_f32_e32 v13, v13, v0
	v_mul_f32_e32 v10, v10, v0
	v_mul_f32_e32 v11, v11, v0
	global_store_dwordx2 v[34:35], v[2:3], off
	v_cvt_pk_bf16_f32 v2, v6, v7
	v_cvt_pk_bf16_f32 v3, v8, v9
	v_mul_f32_e32 v16, v16, v0
	v_mul_f32_e32 v17, v17, v0
	v_mul_f32_e32 v14, v14, v0
	v_mul_f32_e32 v15, v15, v0
	global_store_dwordx2 v[34:35], v[2:3], off offset:16
	v_cvt_pk_bf16_f32 v2, v10, v11
	v_cvt_pk_bf16_f32 v3, v12, v13
	v_mul_f32_e32 v20, v20, v0
	v_mul_f32_e32 v21, v21, v0
	v_mul_f32_e32 v18, v18, v0
	v_mul_f32_e32 v19, v19, v0
	global_store_dwordx2 v[34:35], v[2:3], off offset:32
	v_cvt_pk_bf16_f32 v2, v14, v15
	v_cvt_pk_bf16_f32 v3, v16, v17
	v_mul_f32_e32 v24, v24, v0
	v_mul_f32_e32 v25, v25, v0
	v_mul_f32_e32 v22, v22, v0
	v_mul_f32_e32 v23, v23, v0
	global_store_dwordx2 v[34:35], v[2:3], off offset:48
	v_cvt_pk_bf16_f32 v2, v18, v19
	v_cvt_pk_bf16_f32 v3, v20, v21
	v_mul_f32_e32 v28, v28, v0
	v_mul_f32_e32 v29, v29, v0
	v_mul_f32_e32 v26, v26, v0
	v_mul_f32_e32 v27, v27, v0
	global_store_dwordx2 v[34:35], v[2:3], off offset:64
	v_cvt_pk_bf16_f32 v2, v22, v23
	v_cvt_pk_bf16_f32 v3, v24, v25
	v_mul_f32_e32 v32, v32, v0
	v_mul_f32_e32 v33, v33, v0
	v_mul_f32_e32 v30, v30, v0
	v_mul_f32_e32 v31, v31, v0
	global_store_dwordx2 v[34:35], v[2:3], off offset:80
	v_cvt_pk_bf16_f32 v2, v26, v27
	v_cvt_pk_bf16_f32 v3, v28, v29
	global_store_dwordx2 v[34:35], v[2:3], off offset:96
	v_cvt_pk_bf16_f32 v2, v30, v31
	v_cvt_pk_bf16_f32 v3, v32, v33
	s_mov_b64 s[8:9], 0
	global_store_dwordx2 v[34:35], v[2:3], off offset:112

.LBB0_1145:
	s_waitcnt lgkmcnt(0)
	v_add_f32_e32 v65, v65, v230
	v_cmp_gt_u32_e32 vcc, s46, v187
	v_add_f32_e32 v48, v48, v229
	v_add_f32_e32 v47, v47, v225
	v_cndmask_b32_e32 v187, v137, v65, vcc
	v_cmp_gt_u32_e32 vcc, s46, v228
	v_add_f32_e32 v46, v46, v221
	v_add_f32_e32 v45, v45, v217
	v_cndmask_b32_e32 v228, v137, v48, vcc
	v_add_f32_e32 v48, v64, v227
	v_cmp_gt_u32_e32 vcc, s46, v226
	v_add_f32_e32 v44, v44, v213
	v_add_f32_e32 v43, v43, v209
	v_cndmask_b32_e32 v226, v137, v48, vcc
	v_cmp_gt_u32_e32 vcc, s46, v224
	v_add_f32_e32 v42, v42, v205
	v_add_f32_e32 v41, v41, v201
	v_cndmask_b32_e32 v224, v137, v47, vcc
	v_add_f32_e32 v47, v63, v223
	v_cmp_gt_u32_e32 vcc, s46, v222
	v_add_f32_e32 v40, v40, v197
	v_add_f32_e32 v39, v39, v193
	v_cndmask_b32_e32 v64, v137, v47, vcc
	v_cmp_gt_u32_e32 vcc, s46, v220
	v_add_f32_e32 v38, v38, v189
	v_add_f32_e32 v37, v37, v183
	v_cndmask_b32_e32 v220, v137, v46, vcc
	v_add_f32_e32 v46, v62, v219
	v_cmp_gt_u32_e32 vcc, s46, v218
	v_add_f32_e32 v36, v36, v179
	v_add_f32_e32 v35, v35, v175
	v_cndmask_b32_e32 v62, v137, v46, vcc
	v_cmp_gt_u32_e32 vcc, s46, v216
	v_add_f32_e32 v34, v34, v171
	v_add_f32_e32 v0, v49, v0
	v_cndmask_b32_e32 v48, v137, v45, vcc
	v_add_f32_e32 v45, v61, v215
	v_cmp_gt_u32_e32 vcc, s46, v214
	s_nop 1
	v_cndmask_b32_e32 v214, v137, v45, vcc
	v_cmp_gt_u32_e32 vcc, s46, v212
	s_nop 1
	v_cndmask_b32_e32 v47, v137, v44, vcc
	v_add_f32_e32 v44, v60, v211
	v_cmp_gt_u32_e32 vcc, s46, v210
	s_nop 1
	v_cndmask_b32_e32 v60, v137, v44, vcc
	v_cmp_gt_u32_e32 vcc, s46, v208
	s_nop 1
	v_cndmask_b32_e32 v45, v137, v43, vcc
	v_add_f32_e32 v43, v59, v207
	v_cmp_gt_u32_e32 vcc, s46, v206
	s_nop 1
	v_cndmask_b32_e32 v206, v137, v43, vcc
	v_cmp_gt_u32_e32 vcc, s46, v204
	s_nop 1
	v_cndmask_b32_e32 v43, v137, v42, vcc
	v_add_f32_e32 v42, v58, v203
	v_cmp_gt_u32_e32 vcc, s46, v202
	s_nop 1
	v_cndmask_b32_e32 v58, v137, v42, vcc
	v_cmp_gt_u32_e32 vcc, s46, v200
	s_nop 1
	v_cndmask_b32_e32 v46, v137, v41, vcc
	v_add_f32_e32 v41, v57, v199
	v_cmp_gt_u32_e32 vcc, s46, v198
	s_nop 1
	v_cndmask_b32_e32 v198, v137, v41, vcc
	v_cmp_gt_u32_e32 vcc, s46, v196
	s_nop 1
	v_cndmask_b32_e32 v44, v137, v40, vcc
	v_add_f32_e32 v40, v56, v195
	v_cmp_gt_u32_e32 vcc, s46, v194
	s_nop 1
	v_cndmask_b32_e32 v56, v137, v40, vcc
	v_cmp_gt_u32_e32 vcc, s46, v192
	s_nop 1
	v_cndmask_b32_e32 v42, v137, v39, vcc
	v_add_f32_e32 v39, v55, v191
	v_cmp_gt_u32_e32 vcc, s46, v190
	s_nop 1
	v_cndmask_b32_e32 v55, v137, v39, vcc
	v_cmp_gt_u32_e32 vcc, s46, v188
	s_nop 1
	v_cndmask_b32_e32 v41, v137, v38, vcc
	v_add_f32_e32 v38, v54, v185
	v_cmp_gt_u32_e32 vcc, s46, v184
	s_nop 1
	v_cndmask_b32_e32 v61, v137, v38, vcc
	v_cmp_gt_u32_e32 vcc, s46, v182
	v_add_f32_e32 v38, v53, v181
	s_nop 0
	v_cndmask_b32_e32 v37, v137, v37, vcc
	v_cmp_gt_u32_e32 vcc, s46, v180
	s_nop 1
	v_cndmask_b32_e32 v40, v137, v38, vcc
	v_cmp_gt_u32_e32 vcc, s46, v178
	v_add_f32_e32 v38, v52, v177
	s_nop 0
	v_cndmask_b32_e32 v36, v137, v36, vcc
	v_cmp_gt_u32_e32 vcc, s46, v176
	s_nop 1
	v_cndmask_b32_e32 v39, v137, v38, vcc
	v_cmp_gt_u32_e32 vcc, s46, v174
	s_nop 1
	v_cndmask_b32_e32 v38, v137, v35, vcc
	v_add_f32_e32 v35, v51, v173
	v_cmp_gt_u32_e32 vcc, s46, v172
	s_nop 1
	v_cndmask_b32_e32 v52, v137, v35, vcc
	v_cmp_gt_u32_e32 vcc, s46, v170
	s_nop 1
	v_cndmask_b32_e32 v35, v137, v34, vcc
	v_add_f32_e32 v34, v50, v169
	v_cmp_gt_u32_e32 vcc, s46, v168
	s_nop 1
	v_cndmask_b32_e32 v50, v137, v34, vcc
	v_max3_f32 v34, v137, v50, v35
	v_cmp_gt_u32_e32 vcc, s46, v186
	v_max3_f32 v34, v34, v52, v38
	v_max3_f32 v34, v34, v39, v36
	v_max3_f32 v34, v34, v40, v37
	v_cndmask_b32_e32 v0, v137, v0, vcc
	v_max3_f32 v34, v34, v61, v41
	v_max3_f32 v34, v34, v55, v42
	v_max3_f32 v34, v34, v56, v44
	v_max3_f32 v34, v34, v198, v46
	v_max3_f32 v34, v34, v58, v43
	v_max3_f32 v34, v34, v206, v45
	v_max3_f32 v34, v34, v60, v47
	v_max3_f32 v34, v34, v214, v48
	v_max3_f32 v34, v34, v62, v220
	v_max3_f32 v34, v34, v64, v224
	v_max3_f32 v34, v34, v226, v228
	v_max3_f32 v34, v34, v187, v0
	ds_bpermute_b32 v49, v161, v34
	v_max_f32_e32 v34, v34, v34
	s_waitcnt lgkmcnt(0)
	v_max_f32_e32 v49, v49, v49
	v_max_f32_e32 v171, v34, v49
	v_max_f32_e32 v34, v166, v166
	v_max_f32_e32 v34, v34, v171
	v_sub_f32_e32 v49, v50, v34
	v_sub_f32_e32 v35, v35, v34
	v_exp_f32_e32 v51, v49
	v_exp_f32_e32 v35, v35
	v_sub_f32_e32 v49, v52, v34
	v_sub_f32_e32 v38, v38, v34
	v_exp_f32_e32 v54, v49
	v_exp_f32_e32 v38, v38
	v_sub_f32_e32 v39, v39, v34
	v_sub_f32_e32 v36, v36, v34
	v_add_f32_e32 v49, v51, v35
	v_exp_f32_e32 v57, v39
	v_exp_f32_e32 v39, v36
	v_sub_f32_e32 v36, v40, v34
	v_add_f32_e32 v49, 0, v49
	v_add_f32_e32 v50, v54, v38
	v_exp_f32_e32 v59, v36
	v_sub_f32_e32 v36, v37, v34
	v_exp_f32_e32 v40, v36
	v_add_f32_e32 v36, v50, v49
	v_sub_f32_e32 v49, v61, v34
	v_exp_f32_e32 v61, v49
	v_sub_f32_e32 v41, v41, v34
	v_sub_f32_e32 v49, v55, v34
	v_exp_f32_e32 v41, v41
	v_exp_f32_e32 v63, v49
	v_sub_f32_e32 v42, v42, v34
	v_sub_f32_e32 v49, v56, v34
	v_exp_f32_e32 v42, v42
	v_exp_f32_e32 v65, v49
	v_sub_f32_e32 v44, v44, v34
	v_sub_f32_e32 v49, v198, v34
	v_add_f32_e32 v37, v57, v39
	v_exp_f32_e32 v44, v44
	v_exp_f32_e32 v169, v49
	v_sub_f32_e32 v46, v46, v34
	v_sub_f32_e32 v49, v58, v34
	v_add_f32_e32 v36, v37, v36
	v_add_f32_e32 v37, v59, v40
	v_exp_f32_e32 v46, v46
	v_exp_f32_e32 v52, v49
	v_sub_f32_e32 v43, v43, v34
	v_sub_f32_e32 v49, v206, v34
	v_add_f32_e32 v36, v37, v36
	v_add_f32_e32 v37, v61, v41
	v_exp_f32_e32 v43, v43
	v_exp_f32_e32 v55, v49
	v_sub_f32_e32 v45, v45, v34
	v_sub_f32_e32 v49, v60, v34
	v_add_f32_e32 v36, v37, v36
	v_add_f32_e32 v37, v63, v42
	v_exp_f32_e32 v45, v45
	v_exp_f32_e32 v58, v49
	v_sub_f32_e32 v47, v47, v34
	v_sub_f32_e32 v49, v214, v34
	v_add_f32_e32 v36, v37, v36
	v_add_f32_e32 v37, v65, v44
	v_exp_f32_e32 v47, v47
	v_exp_f32_e32 v60, v49
	v_sub_f32_e32 v48, v48, v34
	v_sub_f32_e32 v49, v62, v34
	v_add_f32_e32 v36, v37, v36
	v_add_f32_e32 v37, v169, v46
	v_exp_f32_e32 v48, v48
	v_exp_f32_e32 v62, v49
	v_sub_f32_e32 v49, v220, v34
	v_sub_f32_e32 v50, v64, v34
	v_add_f32_e32 v36, v37, v36
	v_add_f32_e32 v37, v52, v43
	v_exp_f32_e32 v49, v49
	v_exp_f32_e32 v64, v50
	v_sub_f32_e32 v50, v224, v34
	v_sub_f32_e32 v53, v226, v34
	v_add_f32_e32 v36, v37, v36
	v_add_f32_e32 v37, v55, v45
	v_exp_f32_e32 v50, v50
	v_exp_f32_e32 v168, v53
	v_sub_f32_e32 v53, v228, v34
	v_add_f32_e32 v36, v37, v36
	v_add_f32_e32 v37, v58, v47
	v_exp_f32_e32 v53, v53
	v_sub_f32_e32 v56, v187, v34
	v_sub_f32_e32 v0, v0, v34
	v_add_f32_e32 v36, v37, v36
	v_add_f32_e32 v37, v60, v48
	v_exp_f32_e32 v170, v56
	v_exp_f32_e32 v56, v0
	v_add_f32_e32 v36, v37, v36
	v_add_f32_e32 v37, v62, v49
	v_add_f32_e32 v36, v37, v36
	v_add_f32_e32 v37, v64, v50
	v_add_f32_e32 v0, v37, v36
	v_add_f32_e32 v36, v168, v53
	v_add_f32_e32 v0, v36, v0
	v_add_f32_e32 v36, v170, v56
	v_add_f32_e32 v36, v36, v0
	v_sub_f32_e32 v172, v166, v34
	ds_bpermute_b32 v37, v161, v36
	v_exp_f32_e32 v0, v172
	v_cmp_gt_f32_e32 vcc, v171, v166
	s_cbranch_vccz .LBB0_1147
	v_mul_f32_e32 v32, v32, v0
	v_mul_f32_e32 v33, v33, v0
	v_mul_f32_e32 v30, v30, v0
	v_mul_f32_e32 v31, v31, v0
	v_mul_f32_e32 v28, v28, v0
	v_mul_f32_e32 v29, v29, v0
	v_mul_f32_e32 v26, v26, v0
	v_mul_f32_e32 v27, v27, v0
	v_mul_f32_e32 v24, v24, v0
	v_mul_f32_e32 v25, v25, v0
	v_mul_f32_e32 v22, v22, v0
	v_mul_f32_e32 v23, v23, v0
	v_mul_f32_e32 v20, v20, v0
	v_mul_f32_e32 v21, v21, v0
	v_mul_f32_e32 v18, v18, v0
	v_mul_f32_e32 v19, v19, v0
	v_mul_f32_e32 v16, v16, v0
	v_mul_f32_e32 v17, v17, v0
	v_mul_f32_e32 v14, v14, v0
	v_mul_f32_e32 v15, v15, v0
	v_mul_f32_e32 v12, v12, v0
	v_mul_f32_e32 v13, v13, v0
	v_mul_f32_e32 v10, v10, v0
	v_mul_f32_e32 v11, v11, v0
	v_mul_f32_e32 v8, v8, v0
	v_mul_f32_e32 v9, v9, v0
	v_mul_f32_e32 v6, v6, v0
	v_mul_f32_e32 v7, v7, v0
	v_mul_f32_e32 v4, v4, v0
	v_mul_f32_e32 v5, v5, v0
	v_mul_f32_e32 v2, v2, v0
	v_mul_f32_e32 v3, v3, v0

.LBB0_1240:
	global_load_ushort v0, v[136:137], off offset:4
	v_lshlrev_b64 v[72:73], 12, v[132:133]
	v_mov_b32_e32 v44, v35
	v_mov_b32_e32 v35, v47
	v_lshl_add_u64 v[46:47], s[24:25], 0, v[72:73]
	s_mov_b32 s73, s67
	v_ashrrev_i32_e32 v131, 31, v130
	v_lshl_add_u64 v[46:47], v[46:47], 0, s[72:73]
	s_mov_b64 s[8:9], 0x11c98800
	v_lshl_add_u64 v[46:47], v[130:131], 1, v[46:47]
	v_mov_b32_e32 v41, v51
	v_mov_b32_e32 v71, v52
	v_pk_mov_b32 v[50:51], v[52:53], v[50:51] op_sel:[1,0]
	v_lshl_add_u64 v[52:53], v[46:47], 0, s[8:9]
	s_mov_b32 s7, 0x11c98000
	ds_read2st64_b32 v[56:57], v200 offset0:168 offset1:176
	ds_read2st64_b32 v[58:59], v199 offset0:128 offset1:136
	ds_read2st64_b32 v[60:61], v200 offset0:184 offset1:192
	ds_read2st64_b32 v[62:63], v199 offset0:144 offset1:152
	ds_read2st64_b32 v[64:65], v200 offset0:200 offset1:208
	ds_read2st64_b32 v[66:67], v199 offset0:160 offset1:168
	ds_read2st64_b32 v[68:69], v200 offset0:216 offset1:224
	ds_read_b32 v70, v199 offset:45056
	s_waitcnt vmcnt(0)
	v_lshlrev_b32_e32 v0, 16, v0
	v_mul_f32_e32 v0, 0xbfb8aa3b, v0
	v_exp_f32_e32 v0, v0
	s_nop 0
	v_add_f32_e32 v0, 1.0, v0
	v_div_scale_f32 v55, s[10:11], v0, v0, 1.0
	v_rcp_f32_e32 v72, v55
	v_div_scale_f32 v73, vcc, 1.0, v0, 1.0
	v_fma_f32 v74, -v55, v72, 1.0
	v_fmac_f32_e32 v72, v74, v72
	v_mul_f32_e32 v74, v73, v72
	v_fma_f32 v75, -v55, v74, v73
	v_fmac_f32_e32 v74, v75, v72
	v_fma_f32 v55, -v55, v74, v73
	v_div_fmas_f32 v55, v55, v72, v74
	v_div_fixup_f32 v0, v55, v0, 1.0
	v_div_scale_f32 v55, s[8:9], v54, v54, v0
	v_rcp_f32_e32 v72, v55
	v_add_co_u32_e32 v46, vcc, s7, v46
	s_mov_b64 s[8:9], 0
	s_nop 0
	v_addc_co_u32_e32 v47, vcc, 0, v47, vcc
	v_fma_f32 v74, -v55, v72, 1.0
	v_div_scale_f32 v73, vcc, v0, v54, v0
	v_fmac_f32_e32 v72, v74, v72
	v_mul_f32_e32 v74, v73, v72
	v_fma_f32 v75, -v55, v74, v73
	v_fmac_f32_e32 v74, v75, v72
	v_fma_f32 v55, -v55, v74, v73
	v_div_fmas_f32 v55, v55, v72, v74
	v_div_fixup_f32 v0, v55, v54, v0
	s_waitcnt lgkmcnt(7)
	v_fma_f32 v2, v2, v0, v56
	v_fma_f32 v3, v3, v0, v57
	s_waitcnt lgkmcnt(5)
	v_fma_f32 v4, v4, v0, v60
	v_fma_f32 v5, v5, v0, v61
	s_waitcnt lgkmcnt(3)
	v_fma_f32 v6, v6, v0, v64
	v_fma_f32 v7, v7, v0, v65
	s_waitcnt lgkmcnt(1)
	v_fma_f32 v8, v8, v0, v68
	v_fma_f32 v9, v9, v0, v69
	v_fma_f32 v10, v10, v0, v40
	v_fma_f32 v11, v11, v0, v41
	v_fma_f32 v12, v12, v0, v44
	v_fma_f32 v13, v13, v0, v45
	v_fma_f32 v14, v14, v0, v42
	v_fma_f32 v15, v15, v0, v43
	v_fma_f32 v16, v16, v0, v48
	v_fma_f32 v17, v17, v0, v49
	v_fma_f32 v18, v18, v0, v58
	v_fma_f32 v19, v19, v0, v59
	v_fma_f32 v20, v20, v0, v62
	v_fma_f32 v21, v21, v0, v63
	v_fma_f32 v22, v22, v0, v66
	v_fma_f32 v23, v23, v0, v67
	s_waitcnt lgkmcnt(0)
	v_fma_f32 v24, v24, v0, v70
	v_fma_f32 v25, v25, v0, v71
	v_fma_f32 v26, v26, v0, v50
	v_fma_f32 v27, v27, v0, v51
	v_fma_f32 v28, v28, v0, v34
	v_fma_f32 v29, v29, v0, v35
	v_fma_f32 v30, v30, v0, v38
	v_fma_f32 v31, v31, v0, v39
	v_fma_f32 v32, v32, v0, v36
	v_fma_f32 v33, v33, v0, v37
	v_cvt_pk_bf16_f32 v2, v2, v3
	v_cvt_pk_bf16_f32 v3, v4, v5
	v_cvt_pk_bf16_f32 v4, v6, v7
	v_cvt_pk_bf16_f32 v5, v8, v9
	v_cvt_pk_bf16_f32 v6, v10, v11
	v_cvt_pk_bf16_f32 v7, v12, v13
	v_cvt_pk_bf16_f32 v8, v14, v15
	v_cvt_pk_bf16_f32 v9, v16, v17
	v_cvt_pk_bf16_f32 v10, v18, v19
	v_cvt_pk_bf16_f32 v11, v20, v21
	v_cvt_pk_bf16_f32 v12, v22, v23
	v_cvt_pk_bf16_f32 v13, v24, v25
	v_cvt_pk_bf16_f32 v14, v26, v27
	v_cvt_pk_bf16_f32 v15, v28, v29
	v_cvt_pk_bf16_f32 v16, v30, v31
	v_cvt_pk_bf16_f32 v17, v32, v33
	global_store_dwordx2 v[46:47], v[2:3], off offset:2048
	global_store_dwordx2 v[52:53], v[4:5], off offset:16
	global_store_dwordx2 v[52:53], v[6:7], off offset:32
	global_store_dwordx2 v[52:53], v[8:9], off offset:48
	global_store_dwordx2 v[52:53], v[10:11], off offset:64
	global_store_dwordx2 v[52:53], v[12:13], off offset:80
	global_store_dwordx2 v[52:53], v[14:15], off offset:96
	global_store_dwordx2 v[52:53], v[16:17], off offset:112

.LBB0_1252:
	s_or_b64 exec, exec, s[8:9]
	s_lshl_b32 s8, s7, 3
	s_or_b32 s8, s8, s56
	s_bfe_u32 s66, s8, 0x30001
	v_ashrrev_i32_e32 v86, 3, v87
	v_lshl_add_u32 v2, s66, 7, v86
	v_lshlrev_b32_e32 v0, 4, v84
	v_ashrrev_i32_e32 v3, 31, v2
	v_and_b32_e32 v131, 0x70, v0
	v_lshlrev_b64 v[10:11], 8, v[2:3]
	s_lshl_b32 s46, s6, 1
	v_or3_b32 v10, v131, s46, v10
	s_mov_b64 s[8:9], 0x4000
	v_lshl_add_u64 v[2:3], s[58:59], 0, v[10:11]
	v_lshl_add_u64 v[6:7], s[60:61], 0, v[10:11]
	v_lshl_add_u64 v[10:11], v[10:11], 0, s[8:9]
	v_lshl_add_u64 v[12:13], s[58:59], 0, v[10:11]
	v_lshl_add_u64 v[14:15], s[60:61], 0, v[10:11]
	global_load_dwordx4 v[2:5], v[2:3], off
	s_nop 0
	global_load_dwordx4 v[6:9], v[6:7], off
	s_nop 0
	global_load_dwordx4 v[10:13], v[12:13], off
	s_nop 0
	global_load_dwordx4 v[14:17], v[14:15], off
	s_lshl_b32 s7, s7, 4
	s_andn2_b32 s7, s7, 31
	s_sub_i32 s16, 0x7e0, s7
	v_and_b32_e32 v85, 31, v84
	v_or_b32_e32 v193, s16, v85
	v_ashrrev_i32_e32 v0, 5, v84
	v_lshl_add_u32 v132, s66, 11, v193
	v_mov_b64_e32 v[18:19], s[50:51]
	v_mad_i64_i32 v[82:83], s[8:9], v132, s84, v[18:19]
	s_lshl_b32 s72, s34, 1
	s_mov_b32 s73, s67
	v_lshlrev_b32_e32 v20, 3, v0
	v_lshl_add_u64 v[18:19], v[82:83], 0, s[72:73]
	v_ashrrev_i32_e32 v21, 31, v20
	v_lshl_add_u64 v[18:19], v[20:21], 1, v[18:19]
	global_load_dwordx4 v[98:101], v[18:19], off offset:2560
	global_load_dwordx4 v[102:105], v[18:19], off offset:2592
	global_load_dwordx4 v[106:109], v[18:19], off offset:2624
	global_load_dwordx4 v[110:113], v[18:19], off offset:2656
	v_lshrrev_b32_e32 v18, 2, v84
	v_lshlrev_b32_e32 v130, 2, v0
	v_mul_lo_u32 v194, v86, s86
	v_mul_lo_u32 v21, v86, 48
	v_and_or_b32 v22, v18, 3, v130
	v_add_u32_e32 v18, 0, v194
	v_lshlrev_b32_e32 v19, 1, v84
	v_add_u32_e32 v135, v18, v131
	v_add_u32_e32 v18, v18, v21
	s_movk_i32 s8, 0xffd0
	v_and_b32_e32 v20, 32, v19
	v_mad_u32_u24 v19, v85, s86, 0
	v_lshlrev_b32_e32 v195, 4, v0
	v_add_u32_e32 v134, v18, v131
	v_add_u32_e32 v42, v19, v195
	v_mad_u64_u32 v[18:19], s[8:9], v86, s8, v[134:135]
	v_add_u32_e32 v19, v18, v21
	s_waitcnt vmcnt(7)
	ds_write_b128 v135, v[2:5]
	s_waitcnt vmcnt(6)
	ds_write_b128 v134, v[6:9] offset:9216
	s_waitcnt vmcnt(5)
	ds_write_b128 v18, v[10:13] offset:21504
	s_waitcnt vmcnt(4)
	ds_write_b128 v19, v[14:17] offset:30720
	v_mov_b32_e32 v242, 0x1affc
	v_mov_b32_e32 v243, 0xf149f2ca
	ds_write_b32 v242, v243
	s_waitcnt lgkmcnt(0)
	s_barrier
	ds_read_b128 v[2:5], v42
	ds_read_b128 v[34:37], v42 offset:32
	ds_read_b128 v[6:9], v42 offset:4608
	ds_read_b128 v[38:41], v42 offset:4640
	ds_read_b128 v[44:47], v42 offset:64
	ds_read_b128 v[48:51], v42 offset:96
	ds_read_b128 v[52:55], v42 offset:4672
	ds_read_b128 v[56:59], v42 offset:4704
	v_lshlrev_b32_e32 v10, 3, v84
	v_and_b32_e32 v10, 24, v10
	v_mul_lo_u32 v11, v22, s85
	v_or3_b32 v196, v11, v20, v10
	s_waitcnt vmcnt(3) lgkmcnt(7)
	v_mfma_f32_32x32x16_bf16 v[18:33], v[2:5], v[98:101], 0
	s_waitcnt lgkmcnt(5)
	v_mfma_f32_32x32x16_bf16 v[2:17], v[6:9], v[98:101], 0
	s_waitcnt vmcnt(2)
	v_mfma_f32_32x32x16_bf16 v[18:33], v[34:37], v[102:105], v[18:33]
	s_waitcnt lgkmcnt(4)
	v_mfma_f32_32x32x16_bf16 v[2:17], v[38:41], v[102:105], v[2:17]
	s_waitcnt vmcnt(1) lgkmcnt(3)
	v_mfma_f32_32x32x16_bf16 v[18:33], v[44:47], v[106:109], v[18:33]
	v_add_u32_e32 v89, 0, v196
	ds_read_b64_tr_b16 v[34:35], v89 offset:9216
	ds_read_b64_tr_b16 v[36:37], v89 offset:10752
	ds_read_b64_tr_b16 v[40:41], v89 offset:10816
	ds_read_b64_tr_b16 v[38:39], v89 offset:9280
	v_subrev_u32_e32 v88, 31, v193
	v_lshlrev_b32_e32 v45, 6, v0
	v_sub_u32_e32 v46, v88, v45
	v_cmp_lt_i32_e32 vcc, -1, v46
	v_cmp_gt_i32_e64 s[8:9], 32, v0
	s_waitcnt lgkmcnt(5)
	v_mfma_f32_32x32x16_bf16 v[2:17], v[52:55], v[106:109], v[2:17]
	s_and_b64 s[10:11], s[8:9], vcc
	v_mov_b32_e32 v43, 0xf149f2ca
	v_mov_b32_e32 v44, 0xf149f2ca
	s_waitcnt vmcnt(0)
	s_add_i32 s100, s70, 0x1800
	s_mov_b32 s101, 0
	v_lshl_add_u64 v[244:245], v[82:83], 0, s[100:101]
	global_load_ushort v246, v[244:245], off
	v_mfma_f32_32x32x16_bf16 v[18:33], v[48:51], v[110:113], v[18:33]
	s_waitcnt lgkmcnt(4)
	v_mfma_f32_32x32x16_bf16 v[2:17], v[56:59], v[110:113], v[2:17]
	v_min_u32_e32 v210, 0x7f, v46
	v_lshl_add_u32 v210, v210, 2, s3
	v_cndmask_b32_e64 v210, v242, v210, s[10:11]
	ds_read_b32 v210, v210
	v_sub_u32_e32 v74, v193, v45
	v_add_u32_e32 v150, 0xfffffde1, v74
	v_cmp_lt_i32_e64 s[8:9], -1, v150
	v_cmp_gt_i32_e32 vcc, 24, v0
	s_and_b64 s[10:11], vcc, s[8:9]
	v_min_u32_e32 v211, 0x7f, v150
	v_lshl_add_u32 v211, v211, 2, s3
	v_cndmask_b32_e64 v211, v242, v211, s[10:11]
	ds_read_b32 v211, v211
	v_or_b32_e32 v151, 1, v130
	v_lshlrev_b32_e32 v152, 4, v151
	v_sub_u32_e32 v45, v88, v152
	v_cmp_lt_i32_e64 s[8:9], -1, v45
	v_cmp_gt_i32_e64 s[10:11], s82, v151
	s_and_b64 s[10:11], s[10:11], s[8:9]
	v_min_u32_e32 v212, 0x7f, v45
	v_lshl_add_u32 v212, v212, 2, s3
	v_cndmask_b32_e64 v212, v242, v212, s[10:11]
	ds_read_b32 v212, v212
	v_add_u32_e32 v153, 0xfffffdd1, v74
	v_cmp_lt_i32_e64 s[8:9], -1, v153
	s_and_b64 s[10:11], vcc, s[8:9]
	v_min_u32_e32 v213, 0x7f, v153
	v_lshl_add_u32 v213, v213, 2, s3
	v_cndmask_b32_e64 v213, v242, v213, s[10:11]
	ds_read_b32 v213, v213
	v_or_b32_e32 v154, 2, v130
	v_lshlrev_b32_e32 v155, 4, v154
	v_sub_u32_e32 v45, v88, v155
	v_cmp_lt_i32_e64 s[8:9], -1, v45
	v_cmp_gt_i32_e64 s[10:11], s82, v154
	s_and_b64 s[10:11], s[10:11], s[8:9]
	v_min_u32_e32 v214, 0x7f, v45
	v_lshl_add_u32 v214, v214, 2, s3
	v_cndmask_b32_e64 v214, v242, v214, s[10:11]
	ds_read_b32 v214, v214
	v_add_u32_e32 v156, 0xfffffdc1, v74
	v_cmp_lt_i32_e64 s[8:9], -1, v156
	s_and_b64 s[10:11], vcc, s[8:9]
	v_min_u32_e32 v215, 0x7f, v156
	v_lshl_add_u32 v215, v215, 2, s3
	v_cndmask_b32_e64 v215, v242, v215, s[10:11]
	ds_read_b32 v215, v215
	v_or_b32_e32 v157, 3, v130
	v_lshlrev_b32_e32 v158, 4, v157
	v_sub_u32_e32 v45, v88, v158
	v_cmp_lt_i32_e32 vcc, -1, v45
	v_cmp_gt_i32_e64 s[8:9], s82, v157
	s_and_b64 s[10:11], s[8:9], vcc
	v_min_u32_e32 v216, 0x7f, v45
	v_lshl_add_u32 v216, v216, 2, s3
	v_cndmask_b32_e64 v216, v242, v216, s[10:11]
	ds_read_b32 v216, v216
	v_add_u32_e32 v159, 0xfffffdb1, v74
	v_cmp_lt_i32_e32 vcc, -1, v159
	v_cmp_gt_i32_e64 s[8:9], 23, v0
	s_and_b64 s[10:11], s[8:9], vcc
	v_min_u32_e32 v217, 0x7f, v159
	v_lshl_add_u32 v217, v217, 2, s3
	v_cndmask_b32_e64 v217, v242, v217, s[10:11]
	ds_read_b32 v217, v217
	v_add_u32_e32 v45, 0xffffff61, v74
	v_cmp_lt_i32_e64 s[8:9], -1, v45
	v_cmp_gt_i32_e32 vcc, 30, v0
	s_and_b64 s[10:11], vcc, s[8:9]
	v_min_u32_e32 v218, 0x7f, v45
	v_lshl_add_u32 v218, v218, 2, s3
	v_cndmask_b32_e64 v218, v242, v218, s[10:11]
	ds_read_b32 v218, v218
	v_add_u32_e32 v160, 0xfffffd61, v74
	v_cmp_lt_i32_e64 s[10:11], -1, v160
	v_cmp_gt_i32_e64 s[8:9], 22, v0
	s_and_b64 s[12:13], s[8:9], s[10:11]
	v_min_u32_e32 v219, 0x7f, v160
	v_lshl_add_u32 v219, v219, 2, s3
	v_cndmask_b32_e64 v219, v242, v219, s[12:13]
	ds_read_b32 v219, v219
	v_add_u32_e32 v45, 0xffffff51, v74
	v_cmp_lt_i32_e64 s[10:11], -1, v45
	s_and_b64 s[12:13], vcc, s[10:11]
	v_min_u32_e32 v220, 0x7f, v45
	v_lshl_add_u32 v220, v220, 2, s3
	v_cndmask_b32_e64 v220, v242, v220, s[12:13]
	ds_read_b32 v220, v220
	v_add_u32_e32 v161, 0xfffffd51, v74
	v_cmp_lt_i32_e64 s[10:11], -1, v161
	s_and_b64 s[12:13], s[8:9], s[10:11]
	v_min_u32_e32 v221, 0x7f, v161
	v_lshl_add_u32 v221, v221, 2, s3
	v_cndmask_b32_e64 v221, v242, v221, s[12:13]
	ds_read_b32 v221, v221
	v_add_u32_e32 v45, 0xffffff41, v74
	v_cmp_lt_i32_e64 s[10:11], -1, v45
	s_and_b64 s[12:13], vcc, s[10:11]
	v_min_u32_e32 v222, 0x7f, v45
	v_lshl_add_u32 v222, v222, 2, s3
	v_cndmask_b32_e64 v222, v242, v222, s[12:13]
	ds_read_b32 v222, v222
	v_add_u32_e32 v162, 0xfffffd41, v74
	v_cmp_lt_i32_e32 vcc, -1, v162
	s_and_b64 s[10:11], s[8:9], vcc
	v_min_u32_e32 v223, 0x7f, v162
	v_lshl_add_u32 v223, v223, 2, s3
	v_cndmask_b32_e64 v223, v242, v223, s[10:11]
	ds_read_b32 v223, v223
	v_add_u32_e32 v45, 0xffffff31, v74
	v_cmp_lt_i32_e32 vcc, -1, v45
	v_cmp_gt_i32_e64 s[8:9], 29, v0
	s_and_b64 s[10:11], s[8:9], vcc
	v_min_u32_e32 v224, 0x7f, v45
	v_lshl_add_u32 v224, v224, 2, s3
	v_cndmask_b32_e64 v224, v242, v224, s[10:11]
	ds_read_b32 v224, v224
	v_add_u32_e32 v163, 0xfffffd31, v74
	v_cmp_lt_i32_e32 vcc, -1, v163
	v_cmp_gt_i32_e64 s[8:9], 21, v0
	s_and_b64 s[10:11], s[8:9], vcc
	v_min_u32_e32 v225, 0x7f, v163
	v_lshl_add_u32 v225, v225, 2, s3
	v_cndmask_b32_e64 v225, v242, v225, s[10:11]
	ds_read_b32 v225, v225
	v_add_u32_e32 v45, 0xfffffee1, v74
	v_cmp_lt_i32_e64 s[8:9], -1, v45
	v_cmp_gt_i32_e32 vcc, 28, v0
	s_and_b64 s[10:11], vcc, s[8:9]
	v_min_u32_e32 v226, 0x7f, v45
	v_lshl_add_u32 v226, v226, 2, s3
	v_cndmask_b32_e64 v226, v242, v226, s[10:11]
	ds_read_b32 v226, v226
	v_add_u32_e32 v164, 0xfffffce1, v74
	v_cmp_lt_i32_e64 s[10:11], -1, v164
	v_cmp_gt_i32_e64 s[8:9], 20, v0
	s_and_b64 s[12:13], s[8:9], s[10:11]
	v_min_u32_e32 v227, 0x7f, v164
	v_lshl_add_u32 v227, v227, 2, s3
	v_cndmask_b32_e64 v227, v242, v227, s[12:13]
	ds_read_b32 v227, v227
	v_add_u32_e32 v45, 0xfffffed1, v74
	v_cmp_lt_i32_e64 s[10:11], -1, v45
	s_and_b64 s[12:13], vcc, s[10:11]
	v_min_u32_e32 v228, 0x7f, v45
	v_lshl_add_u32 v228, v228, 2, s3
	v_cndmask_b32_e64 v228, v242, v228, s[12:13]
	ds_read_b32 v228, v228
	v_add_u32_e32 v165, 0xfffffcd1, v74
	v_cmp_lt_i32_e64 s[10:11], -1, v165
	s_and_b64 s[12:13], s[8:9], s[10:11]
	v_min_u32_e32 v229, 0x7f, v165
	v_lshl_add_u32 v229, v229, 2, s3
	v_cndmask_b32_e64 v229, v242, v229, s[12:13]
	ds_read_b32 v229, v229
	v_add_u32_e32 v45, 0xfffffec1, v74
	v_cmp_lt_i32_e64 s[10:11], -1, v45
	s_and_b64 s[12:13], vcc, s[10:11]
	v_min_u32_e32 v230, 0x7f, v45
	v_lshl_add_u32 v230, v230, 2, s3
	v_cndmask_b32_e64 v230, v242, v230, s[12:13]
	ds_read_b32 v230, v230
	v_add_u32_e32 v166, 0xfffffcc1, v74
	v_cmp_lt_i32_e32 vcc, -1, v166
	s_and_b64 s[10:11], s[8:9], vcc
	v_min_u32_e32 v231, 0x7f, v166
	v_lshl_add_u32 v231, v231, 2, s3
	v_cndmask_b32_e64 v231, v242, v231, s[10:11]
	ds_read_b32 v231, v231
	v_add_u32_e32 v45, 0xfffffeb1, v74
	v_cmp_lt_i32_e32 vcc, -1, v45
	v_cmp_gt_i32_e64 s[8:9], 27, v0
	s_and_b64 s[10:11], s[8:9], vcc
	v_min_u32_e32 v232, 0x7f, v45
	v_lshl_add_u32 v232, v232, 2, s3
	v_cndmask_b32_e64 v232, v242, v232, s[10:11]
	ds_read_b32 v232, v232
	v_add_u32_e32 v167, 0xfffffcb1, v74
	v_cmp_lt_i32_e32 vcc, -1, v167
	v_cmp_gt_i32_e64 s[8:9], 19, v0
	s_and_b64 s[10:11], s[8:9], vcc
	v_min_u32_e32 v233, 0x7f, v167
	v_lshl_add_u32 v233, v233, 2, s3
	v_cndmask_b32_e64 v233, v242, v233, s[10:11]
	ds_read_b32 v233, v233
	v_add_u32_e32 v45, 0xfffffe61, v74
	v_cmp_lt_i32_e64 s[8:9], -1, v45
	v_cmp_gt_i32_e32 vcc, 26, v0
	s_and_b64 s[10:11], vcc, s[8:9]
	v_min_u32_e32 v234, 0x7f, v45
	v_lshl_add_u32 v234, v234, 2, s3
	v_cndmask_b32_e64 v234, v242, v234, s[10:11]
	ds_read_b32 v234, v234
	v_add_u32_e32 v168, 0xfffffc61, v74
	v_cmp_lt_i32_e64 s[10:11], -1, v168
	v_cmp_gt_i32_e64 s[8:9], 18, v0
	s_and_b64 s[12:13], s[8:9], s[10:11]
	v_min_u32_e32 v235, 0x7f, v168
	v_lshl_add_u32 v235, v235, 2, s3
	v_cndmask_b32_e64 v235, v242, v235, s[12:13]
	ds_read_b32 v235, v235
	v_add_u32_e32 v45, 0xfffffe51, v74
	v_cmp_lt_i32_e64 s[10:11], -1, v45
	s_and_b64 s[12:13], vcc, s[10:11]
	v_min_u32_e32 v236, 0x7f, v45
	v_lshl_add_u32 v236, v236, 2, s3
	v_cndmask_b32_e64 v236, v242, v236, s[12:13]
	ds_read_b32 v236, v236
	v_add_u32_e32 v169, 0xfffffc51, v74
	v_cmp_lt_i32_e64 s[10:11], -1, v169
	s_and_b64 s[12:13], s[8:9], s[10:11]
	v_min_u32_e32 v237, 0x7f, v169
	v_lshl_add_u32 v237, v237, 2, s3
	v_cndmask_b32_e64 v237, v242, v237, s[12:13]
	ds_read_b32 v237, v237
	v_add_u32_e32 v45, 0xfffffe41, v74
	v_cmp_lt_i32_e64 s[10:11], -1, v45
	s_and_b64 s[12:13], vcc, s[10:11]
	v_min_u32_e32 v238, 0x7f, v45
	v_lshl_add_u32 v238, v238, 2, s3
	v_cndmask_b32_e64 v238, v242, v238, s[12:13]
	ds_read_b32 v238, v238
	v_add_u32_e32 v170, 0xfffffc41, v74
	v_cmp_lt_i32_e32 vcc, -1, v170
	s_and_b64 s[10:11], s[8:9], vcc
	v_min_u32_e32 v239, 0x7f, v170
	v_lshl_add_u32 v239, v239, 2, s3
	v_cndmask_b32_e64 v239, v242, v239, s[10:11]
	ds_read_b32 v239, v239
	v_add_u32_e32 v45, 0xfffffe31, v74
	v_cmp_lt_i32_e32 vcc, -1, v45
	v_cmp_gt_i32_e64 s[8:9], 25, v0
	s_and_b64 s[10:11], s[8:9], vcc
	v_min_u32_e32 v240, 0x7f, v45
	v_lshl_add_u32 v240, v240, 2, s3
	v_cndmask_b32_e64 v240, v242, v240, s[10:11]
	ds_read_b32 v240, v240
	v_add_u32_e32 v171, 0xfffffc31, v74
	v_cmp_lt_i32_e32 vcc, -1, v171
	v_cmp_gt_i32_e64 s[8:9], 17, v0
	s_and_b64 s[10:11], s[8:9], vcc
	v_min_u32_e32 v241, 0x7f, v171
	v_lshl_add_u32 v241, v241, 2, s3
	v_cndmask_b32_e64 v241, v242, v241, s[10:11]
	ds_read_b32 v241, v241
	s_waitcnt lgkmcnt(0)
	v_add_f32_e32 v44, v18, v210
	v_add_f32_e32 v43, v2, v211
	v_add_f32_e32 v18, v19, v212
	v_add_f32_e32 v2, v3, v213
	v_add_f32_e32 v19, v20, v214
	v_add_f32_e32 v3, v4, v215
	v_add_f32_e32 v20, v21, v216
	v_add_f32_e32 v4, v5, v217
	v_add_f32_e32 v21, v22, v218
	v_add_f32_e32 v5, v6, v219
	v_add_f32_e32 v22, v23, v220
	v_add_f32_e32 v6, v7, v221
	v_add_f32_e32 v23, v24, v222
	v_add_f32_e32 v7, v8, v223
	v_add_f32_e32 v24, v25, v224
	v_add_f32_e32 v8, v9, v225
	v_add_f32_e32 v25, v26, v226
	v_add_f32_e32 v9, v10, v227
	v_add_f32_e32 v26, v27, v228
	v_add_f32_e32 v10, v11, v229
	v_add_f32_e32 v27, v28, v230
	v_add_f32_e32 v11, v12, v231
	v_add_f32_e32 v28, v29, v232
	v_add_f32_e32 v12, v13, v233
	v_add_f32_e32 v29, v30, v234
	v_add_f32_e32 v13, v14, v235
	v_add_f32_e32 v30, v31, v236
	v_add_f32_e32 v14, v15, v237
	v_add_f32_e32 v31, v32, v238
	v_add_f32_e32 v15, v16, v239
	v_add_f32_e32 v32, v33, v240
	v_add_f32_e32 v16, v17, v241
	v_max3_f32 v17, v191, v44, v43
	v_lshlrev_b32_e32 v33, 7, v0
	v_max3_f32 v17, v17, v18, v2
	v_lshlrev_b32_e32 v45, 2, v85
	v_max3_f32 v17, v17, v19, v3
	s_movk_i32 s8, 0x80
	v_max3_f32 v17, v17, v20, v4
	v_bitop3_b32 v197, v33, s8, v45 bitop3:0x36
	v_max3_f32 v17, v17, v21, v5
	v_mov_b32_e32 v79, 0xf149f2ca
	v_max3_f32 v17, v17, v22, v6
	v_max3_f32 v17, v17, v23, v7
	v_max3_f32 v17, v17, v24, v8
	v_max3_f32 v17, v17, v25, v9
	v_max3_f32 v17, v17, v26, v10
	v_max3_f32 v17, v17, v27, v11
	v_max3_f32 v17, v17, v28, v12
	v_max3_f32 v17, v17, v29, v13
	v_max3_f32 v17, v17, v30, v14
	v_max3_f32 v17, v17, v31, v15
	v_max3_f32 v17, v17, v32, v16
	ds_bpermute_b32 v33, v197, v17
	v_max_f32_e32 v17, v17, v17
	s_waitcnt lgkmcnt(0)
	v_max_f32_e32 v33, v33, v33
	v_max_f32_e32 v17, v17, v33
	v_max_f32_e32 v75, 0xf149f2ca, v17
	v_sub_f32_e32 v5, v5, v75
	v_exp_f32_e32 v59, v5
	v_sub_f32_e32 v5, v22, v75
	v_exp_f32_e32 v22, v5
	v_sub_f32_e32 v5, v6, v75
	v_exp_f32_e32 v60, v5
	v_sub_f32_e32 v5, v23, v75
	v_exp_f32_e32 v23, v5
	v_sub_f32_e32 v5, v7, v75
	v_sub_f32_e32 v33, v44, v75
	v_sub_f32_e32 v43, v43, v75
	v_exp_f32_e32 v61, v5
	v_sub_f32_e32 v5, v24, v75
	v_exp_f32_e32 v33, v33
	v_exp_f32_e32 v43, v43
	v_sub_f32_e32 v18, v18, v75
	v_sub_f32_e32 v2, v2, v75
	v_sub_f32_e32 v3, v3, v75
	v_exp_f32_e32 v24, v5
	v_sub_f32_e32 v5, v8, v75
	v_exp_f32_e32 v18, v18
	v_exp_f32_e32 v56, v2
	v_sub_f32_e32 v19, v19, v75
	v_exp_f32_e32 v57, v3
	v_sub_f32_e32 v3, v20, v75
	v_exp_f32_e32 v62, v5
	v_sub_f32_e32 v5, v25, v75
	v_exp_f32_e32 v19, v19
	v_exp_f32_e32 v20, v3
	v_sub_f32_e32 v3, v4, v75
	v_exp_f32_e32 v63, v5
	v_sub_f32_e32 v5, v9, v75
	v_exp_f32_e32 v58, v3
	v_sub_f32_e32 v21, v21, v75
	v_exp_f32_e32 v64, v5
	v_sub_f32_e32 v5, v26, v75
	v_add_f32_e32 v44, v33, v43
	v_exp_f32_e32 v21, v21
	v_exp_f32_e32 v65, v5
	v_sub_f32_e32 v5, v10, v75
	v_add_f32_e32 v44, 0, v44
	v_add_f32_e32 v45, v18, v56
	v_exp_f32_e32 v66, v5
	v_sub_f32_e32 v5, v27, v75
	v_add_f32_e32 v3, v45, v44
	v_add_f32_e32 v4, v19, v57
	v_exp_f32_e32 v67, v5
	v_sub_f32_e32 v5, v11, v75
	v_add_f32_e32 v3, v4, v3
	v_add_f32_e32 v4, v20, v58
	v_exp_f32_e32 v68, v5
	v_sub_f32_e32 v5, v28, v75
	v_add_f32_e32 v3, v4, v3
	v_add_f32_e32 v4, v21, v59
	v_exp_f32_e32 v69, v5
	v_sub_f32_e32 v5, v12, v75
	v_add_f32_e32 v3, v4, v3
	v_add_f32_e32 v4, v22, v60
	v_exp_f32_e32 v70, v5
	v_sub_f32_e32 v5, v29, v75
	v_add_f32_e32 v3, v4, v3
	v_add_f32_e32 v4, v23, v61
	v_exp_f32_e32 v71, v5
	v_sub_f32_e32 v5, v13, v75
	v_add_f32_e32 v3, v4, v3
	v_add_f32_e32 v4, v24, v62
	v_exp_f32_e32 v72, v5
	v_sub_f32_e32 v5, v30, v75
	v_add_f32_e32 v3, v4, v3
	v_add_f32_e32 v4, v63, v64
	v_exp_f32_e32 v73, v5
	v_sub_f32_e32 v5, v14, v75
	v_add_f32_e32 v3, v4, v3
	v_add_f32_e32 v4, v65, v66
	v_exp_f32_e32 v80, v5
	v_add_f32_e32 v3, v4, v3
	v_add_f32_e32 v4, v67, v68
	v_add_f32_e32 v3, v4, v3
	v_add_f32_e32 v4, v69, v70
	v_add_f32_e32 v3, v4, v3
	v_add_f32_e32 v4, v71, v72
	v_add_f32_e32 v3, v4, v3
	v_add_f32_e32 v4, v73, v80
	v_add_f32_e32 v3, v4, v3
	v_sub_f32_e32 v4, v31, v75
	v_exp_f32_e32 v81, v4
	v_sub_f32_e32 v4, v15, v75
	v_exp_f32_e32 v90, v4
	v_sub_f32_e32 v4, v32, v75
	v_exp_f32_e32 v91, v4
	v_sub_f32_e32 v4, v16, v75
	v_exp_f32_e32 v92, v4
	v_sub_f32_e32 v2, 0xf149f2ca, v75
	v_add_f32_e32 v4, v81, v90
	v_add_f32_e32 v3, v4, v3
	v_exp_f32_e32 v2, v2
	v_add_f32_e32 v4, v91, v92
	v_add_f32_e32 v76, v4, v3
	ds_bpermute_b32 v77, v197, v76
	v_cmp_gt_f32_e32 vcc, v17, v79
	s_cmp_lg_u64 vcc, 0
	v_mul_f32_e32 v78, 0, v2
	s_cselect_b64 vcc, -1, 0
	v_cndmask_b32_e32 v2, 0, v78, vcc
	v_mov_b32_e32 v3, v2
	v_mov_b32_e32 v4, v2
	v_mov_b32_e32 v5, v2
	v_mov_b32_e32 v6, v2
	v_mov_b32_e32 v7, v2
	v_mov_b32_e32 v8, v2
	v_mov_b32_e32 v9, v2
	v_mov_b32_e32 v10, v2
	v_mov_b32_e32 v11, v2
	v_mov_b32_e32 v12, v2
	v_mov_b32_e32 v13, v2
	v_mov_b32_e32 v14, v2
	v_mov_b32_e32 v15, v2
	v_mov_b32_e32 v16, v2
	v_mov_b32_e32 v17, v2
	ds_read_b64_tr_b16 v[44:45], v89 offset:12288
	ds_read_b64_tr_b16 v[46:47], v89 offset:13824
	ds_read_b64_tr_b16 v[50:51], v89 offset:13888
	ds_read_b64_tr_b16 v[48:49], v89 offset:12352
	v_cvt_pk_bf16_f32 v52, v33, v18
	v_cvt_pk_bf16_f32 v53, v19, v20
	v_cvt_pk_bf16_f32 v54, v21, v22
	v_cvt_pk_bf16_f32 v55, v23, v24
	s_nop 1
	v_mfma_f32_32x32x16_bf16 v[18:33], v[34:37], v[52:55], v[2:17]
	v_mfma_f32_32x32x16_bf16 v[2:17], v[38:41], v[52:55], v[2:17]
	ds_read_b64_tr_b16 v[34:35], v89 offset:15360
	ds_read_b64_tr_b16 v[36:37], v89 offset:16896
	ds_read_b64_tr_b16 v[40:41], v89 offset:16960
	ds_read_b64_tr_b16 v[38:39], v89 offset:15424
	v_cvt_pk_bf16_f32 v52, v63, v65
	v_cvt_pk_bf16_f32 v53, v67, v69
	v_cvt_pk_bf16_f32 v54, v71, v73
	v_cvt_pk_bf16_f32 v55, v81, v91
	s_waitcnt lgkmcnt(6)
	s_nop 0
	v_mfma_f32_32x32x16_bf16 v[18:33], v[44:47], v[52:55], v[18:33]
	s_waitcnt lgkmcnt(4)
	v_mfma_f32_32x32x16_bf16 v[2:17], v[48:51], v[52:55], v[2:17]
	ds_read_b64_tr_b16 v[44:45], v89 offset:18432
	ds_read_b64_tr_b16 v[46:47], v89 offset:19968
	ds_read_b64_tr_b16 v[50:51], v89 offset:20032
	ds_read_b64_tr_b16 v[48:49], v89 offset:18496
	v_cvt_pk_bf16_f32 v52, v43, v56
	v_cvt_pk_bf16_f32 v53, v57, v58
	v_cvt_pk_bf16_f32 v54, v59, v60
	v_cvt_pk_bf16_f32 v55, v61, v62
	s_waitcnt lgkmcnt(6)
	s_nop 0
	v_mfma_f32_32x32x16_bf16 v[18:33], v[34:37], v[52:55], v[18:33]
	s_waitcnt lgkmcnt(4)
	v_mfma_f32_32x32x16_bf16 v[2:17], v[38:41], v[52:55], v[2:17]
	v_cvt_pk_bf16_f32 v34, v64, v66
	v_cvt_pk_bf16_f32 v35, v68, v70
	v_cvt_pk_bf16_f32 v36, v72, v80
	v_cvt_pk_bf16_f32 v37, v90, v92
	s_waitcnt lgkmcnt(2)
	s_nop 0
	v_mfma_f32_32x32x16_bf16 v[18:33], v[44:47], v[34:37], v[18:33]
	s_waitcnt lgkmcnt(0)
	v_mfma_f32_32x32x16_bf16 v[2:17], v[48:51], v[34:37], v[2:17]
	ds_read_b128 v[34:37], v42 offset:21504
	ds_read_b128 v[66:69], v42 offset:21536
	ds_read_b128 v[38:41], v42 offset:26112
	ds_read_b128 v[70:73], v42 offset:26144
	ds_read_b128 v[90:93], v42 offset:21568
	ds_read_b128 v[94:97], v42 offset:21600
	ds_read_b128 v[114:117], v42 offset:26176
	ds_read_b128 v[118:121], v42 offset:26208
	s_waitcnt lgkmcnt(7)
	v_mfma_f32_32x32x16_bf16 v[50:65], v[34:37], v[98:101], 0
	s_waitcnt lgkmcnt(5)
	v_mfma_f32_32x32x16_bf16 v[34:49], v[38:41], v[98:101], 0
	v_mfma_f32_32x32x16_bf16 v[50:65], v[66:69], v[102:105], v[50:65]
	s_waitcnt lgkmcnt(4)
	v_mfma_f32_32x32x16_bf16 v[34:49], v[70:73], v[102:105], v[34:49]
	s_waitcnt lgkmcnt(3)
	v_mfma_f32_32x32x16_bf16 v[50:65], v[90:93], v[106:109], v[50:65]
	ds_read_b64_tr_b16 v[66:67], v89 offset:30720
	ds_read_b64_tr_b16 v[68:69], v89 offset:32256
	ds_read_b64_tr_b16 v[72:73], v89 offset:32320
	ds_read_b64_tr_b16 v[70:71], v89 offset:30784
	v_add_u32_e32 v81, 0xfffffbe1, v74
	v_cmp_lt_i32_e64 s[8:9], -1, v81
	v_cmp_gt_i32_e32 vcc, 16, v0
	s_and_b64 s[10:11], vcc, s[8:9]
	v_mov_b32_e32 v80, 0xf149f2ca
	s_waitcnt lgkmcnt(5)
	v_mfma_f32_32x32x16_bf16 v[34:49], v[114:117], v[106:109], v[34:49]
	v_mfma_f32_32x32x16_bf16 v[50:65], v[94:97], v[110:113], v[50:65]
	s_waitcnt lgkmcnt(4)
	v_mfma_f32_32x32x16_bf16 v[34:49], v[118:121], v[110:113], v[34:49]
	v_min_u32_e32 v210, 0x7f, v81
	v_lshl_add_u32 v210, v210, 2, s3
	v_cndmask_b32_e64 v210, v242, v210, s[10:11]
	ds_read_b32 v210, v210
	s_nop 6
	v_add_u32_e32 v150, 0xfffff9e1, v74
	v_cmp_lt_i32_e64 s[10:11], -1, v150
	v_cmp_gt_i32_e64 s[8:9], 8, v0
	s_and_b64 s[12:13], s[8:9], s[10:11]
	v_min_u32_e32 v211, 0x7f, v150
	v_lshl_add_u32 v211, v211, 2, s3
	v_cndmask_b32_e64 v211, v242, v211, s[12:13]
	ds_read_b32 v211, v211
	v_add_u32_e32 v81, 0xfffffbd1, v74
	v_cmp_lt_i32_e64 s[10:11], -1, v81
	s_and_b64 s[12:13], vcc, s[10:11]
	v_min_u32_e32 v212, 0x7f, v81
	v_lshl_add_u32 v212, v212, 2, s3
	v_cndmask_b32_e64 v212, v242, v212, s[12:13]
	ds_read_b32 v212, v212
	v_add_u32_e32 v151, 0xfffff9d1, v74
	v_cmp_lt_i32_e64 s[10:11], -1, v151
	s_and_b64 s[12:13], s[8:9], s[10:11]
	v_min_u32_e32 v213, 0x7f, v151
	v_lshl_add_u32 v213, v213, 2, s3
	v_cndmask_b32_e64 v213, v242, v213, s[12:13]
	ds_read_b32 v213, v213
	v_add_u32_e32 v81, 0xfffffbc1, v74
	v_cmp_lt_i32_e64 s[10:11], -1, v81
	s_and_b64 s[12:13], vcc, s[10:11]
	v_min_u32_e32 v214, 0x7f, v81
	v_lshl_add_u32 v214, v214, 2, s3
	v_cndmask_b32_e64 v214, v242, v214, s[12:13]
	ds_read_b32 v214, v214
	v_add_u32_e32 v152, 0xfffff9c1, v74
	v_cmp_lt_i32_e32 vcc, -1, v152
	s_and_b64 s[10:11], s[8:9], vcc
	v_min_u32_e32 v215, 0x7f, v152
	v_lshl_add_u32 v215, v215, 2, s3
	v_cndmask_b32_e64 v215, v242, v215, s[10:11]
	ds_read_b32 v215, v215
	v_add_u32_e32 v81, 0xfffffbb1, v74
	v_cmp_lt_i32_e32 vcc, -1, v81
	v_cmp_gt_i32_e64 s[8:9], 15, v0
	s_and_b64 s[10:11], s[8:9], vcc
	v_min_u32_e32 v216, 0x7f, v81
	v_lshl_add_u32 v216, v216, 2, s3
	v_cndmask_b32_e64 v216, v242, v216, s[10:11]
	ds_read_b32 v216, v216
	v_add_u32_e32 v153, 0xfffff9b1, v74
	v_cmp_lt_i32_e32 vcc, -1, v153
	v_cmp_gt_i32_e64 s[8:9], 7, v0
	s_and_b64 s[10:11], s[8:9], vcc
	v_min_u32_e32 v217, 0x7f, v153
	v_lshl_add_u32 v217, v217, 2, s3
	v_cndmask_b32_e64 v217, v242, v217, s[10:11]
	ds_read_b32 v217, v217
	v_add_u32_e32 v81, 0xfffffb61, v74
	v_cmp_lt_i32_e64 s[8:9], -1, v81
	v_cmp_gt_i32_e32 vcc, 14, v0
	s_and_b64 s[10:11], vcc, s[8:9]
	v_min_u32_e32 v218, 0x7f, v81
	v_lshl_add_u32 v218, v218, 2, s3
	v_cndmask_b32_e64 v218, v242, v218, s[10:11]
	ds_read_b32 v218, v218
	v_add_u32_e32 v154, 0xfffff961, v74
	v_cmp_lt_i32_e64 s[10:11], -1, v154
	v_cmp_gt_i32_e64 s[8:9], 6, v0
	s_and_b64 s[12:13], s[8:9], s[10:11]
	v_min_u32_e32 v219, 0x7f, v154
	v_lshl_add_u32 v219, v219, 2, s3
	v_cndmask_b32_e64 v219, v242, v219, s[12:13]
	ds_read_b32 v219, v219
	v_add_u32_e32 v81, 0xfffffb51, v74
	v_cmp_lt_i32_e64 s[10:11], -1, v81
	s_and_b64 s[12:13], vcc, s[10:11]
	v_min_u32_e32 v220, 0x7f, v81
	v_lshl_add_u32 v220, v220, 2, s3
	v_cndmask_b32_e64 v220, v242, v220, s[12:13]
	ds_read_b32 v220, v220
	v_add_u32_e32 v155, 0xfffff951, v74
	v_cmp_lt_i32_e64 s[10:11], -1, v155
	s_and_b64 s[12:13], s[8:9], s[10:11]
	v_min_u32_e32 v221, 0x7f, v155
	v_lshl_add_u32 v221, v221, 2, s3
	v_cndmask_b32_e64 v221, v242, v221, s[12:13]
	ds_read_b32 v221, v221
	v_add_u32_e32 v81, 0xfffffb41, v74
	v_cmp_lt_i32_e64 s[10:11], -1, v81
	s_and_b64 s[12:13], vcc, s[10:11]
	v_min_u32_e32 v222, 0x7f, v81
	v_lshl_add_u32 v222, v222, 2, s3
	v_cndmask_b32_e64 v222, v242, v222, s[12:13]
	ds_read_b32 v222, v222
	v_add_u32_e32 v156, 0xfffff941, v74
	v_cmp_lt_i32_e32 vcc, -1, v156
	s_and_b64 s[10:11], s[8:9], vcc
	v_min_u32_e32 v223, 0x7f, v156
	v_lshl_add_u32 v223, v223, 2, s3
	v_cndmask_b32_e64 v223, v242, v223, s[10:11]
	ds_read_b32 v223, v223
	v_add_u32_e32 v81, 0xfffffb31, v74
	v_cmp_lt_i32_e32 vcc, -1, v81
	v_cmp_gt_i32_e64 s[8:9], 13, v0
	s_and_b64 s[10:11], s[8:9], vcc
	v_min_u32_e32 v224, 0x7f, v81
	v_lshl_add_u32 v224, v224, 2, s3
	v_cndmask_b32_e64 v224, v242, v224, s[10:11]
	ds_read_b32 v224, v224
	v_add_u32_e32 v157, 0xfffff931, v74
	v_cmp_lt_i32_e32 vcc, -1, v157
	v_cmp_gt_i32_e64 s[8:9], 5, v0
	s_and_b64 s[10:11], s[8:9], vcc
	v_min_u32_e32 v225, 0x7f, v157
	v_lshl_add_u32 v225, v225, 2, s3
	v_cndmask_b32_e64 v225, v242, v225, s[10:11]
	ds_read_b32 v225, v225
	v_add_u32_e32 v81, 0xfffffae1, v74
	v_cmp_lt_i32_e64 s[8:9], -1, v81
	v_cmp_gt_i32_e32 vcc, 12, v0
	s_and_b64 s[10:11], vcc, s[8:9]
	v_min_u32_e32 v226, 0x7f, v81
	v_lshl_add_u32 v226, v226, 2, s3
	v_cndmask_b32_e64 v226, v242, v226, s[10:11]
	ds_read_b32 v226, v226
	v_add_u32_e32 v158, 0xfffff8e1, v74
	v_cmp_lt_i32_e64 s[10:11], -1, v158
	v_cmp_gt_i32_e64 s[8:9], 4, v0
	s_and_b64 s[12:13], s[8:9], s[10:11]
	v_min_u32_e32 v227, 0x7f, v158
	v_lshl_add_u32 v227, v227, 2, s3
	v_cndmask_b32_e64 v227, v242, v227, s[12:13]
	ds_read_b32 v227, v227
	v_add_u32_e32 v81, 0xfffffad1, v74
	v_cmp_lt_i32_e64 s[10:11], -1, v81
	s_and_b64 s[12:13], vcc, s[10:11]
	v_min_u32_e32 v228, 0x7f, v81
	v_lshl_add_u32 v228, v228, 2, s3
	v_cndmask_b32_e64 v228, v242, v228, s[12:13]
	ds_read_b32 v228, v228
	v_add_u32_e32 v159, 0xfffff8d1, v74
	v_cmp_lt_i32_e64 s[10:11], -1, v159
	s_and_b64 s[12:13], s[8:9], s[10:11]
	v_min_u32_e32 v229, 0x7f, v159
	v_lshl_add_u32 v229, v229, 2, s3
	v_cndmask_b32_e64 v229, v242, v229, s[12:13]
	ds_read_b32 v229, v229
	v_add_u32_e32 v81, 0xfffffac1, v74
	v_cmp_lt_i32_e64 s[10:11], -1, v81
	s_and_b64 s[12:13], vcc, s[10:11]
	v_min_u32_e32 v230, 0x7f, v81
	v_lshl_add_u32 v230, v230, 2, s3
	v_cndmask_b32_e64 v230, v242, v230, s[12:13]
	ds_read_b32 v230, v230
	v_add_u32_e32 v160, 0xfffff8c1, v74
	v_cmp_lt_i32_e32 vcc, -1, v160
	s_and_b64 s[10:11], s[8:9], vcc
	v_min_u32_e32 v231, 0x7f, v160
	v_lshl_add_u32 v231, v231, 2, s3
	v_cndmask_b32_e64 v231, v242, v231, s[10:11]
	ds_read_b32 v231, v231
	v_add_u32_e32 v81, 0xfffffab1, v74
	v_cmp_lt_i32_e32 vcc, -1, v81
	v_cmp_gt_i32_e64 s[8:9], 11, v0
	s_and_b64 s[10:11], s[8:9], vcc
	v_min_u32_e32 v232, 0x7f, v81
	v_lshl_add_u32 v232, v232, 2, s3
	v_cndmask_b32_e64 v232, v242, v232, s[10:11]
	ds_read_b32 v232, v232
	v_add_u32_e32 v161, 0xfffff8b1, v74
	v_cmp_lt_i32_e32 vcc, -1, v161
	v_cmp_gt_i32_e64 s[8:9], 3, v0
	s_and_b64 s[10:11], s[8:9], vcc
	v_min_u32_e32 v233, 0x7f, v161
	v_lshl_add_u32 v233, v233, 2, s3
	v_cndmask_b32_e64 v233, v242, v233, s[10:11]
	ds_read_b32 v233, v233
	v_add_u32_e32 v81, 0xfffffa61, v74
	v_cmp_lt_i32_e64 s[8:9], -1, v81
	v_cmp_gt_i32_e32 vcc, 10, v0
	s_and_b64 s[10:11], vcc, s[8:9]
	v_min_u32_e32 v234, 0x7f, v81
	v_lshl_add_u32 v234, v234, 2, s3
	v_cndmask_b32_e64 v234, v242, v234, s[10:11]
	ds_read_b32 v234, v234
	v_add_u32_e32 v162, 0xfffff861, v74
	v_cmp_lt_i32_e64 s[10:11], -1, v162
	v_cmp_gt_i32_e64 s[8:9], 2, v0
	s_and_b64 s[12:13], s[8:9], s[10:11]
	v_min_u32_e32 v235, 0x7f, v162
	v_lshl_add_u32 v235, v235, 2, s3
	v_cndmask_b32_e64 v235, v242, v235, s[12:13]
	ds_read_b32 v235, v235
	v_add_u32_e32 v81, 0xfffffa51, v74
	v_cmp_lt_i32_e64 s[10:11], -1, v81
	s_and_b64 s[12:13], vcc, s[10:11]
	v_min_u32_e32 v236, 0x7f, v81
	v_lshl_add_u32 v236, v236, 2, s3
	v_cndmask_b32_e64 v236, v242, v236, s[12:13]
	ds_read_b32 v236, v236
	v_add_u32_e32 v163, 0xfffff851, v74
	v_cmp_lt_i32_e64 s[10:11], -1, v163
	s_and_b64 s[12:13], s[8:9], s[10:11]
	v_min_u32_e32 v237, 0x7f, v163
	v_lshl_add_u32 v237, v237, 2, s3
	v_cndmask_b32_e64 v237, v242, v237, s[12:13]
	ds_read_b32 v237, v237
	v_add_u32_e32 v81, 0xfffffa41, v74
	v_cmp_lt_i32_e64 s[10:11], -1, v81
	s_and_b64 s[12:13], vcc, s[10:11]
	v_min_u32_e32 v238, 0x7f, v81
	v_lshl_add_u32 v238, v238, 2, s3
	v_cndmask_b32_e64 v238, v242, v238, s[12:13]
	ds_read_b32 v238, v238
	v_add_u32_e32 v164, 0xfffff841, v74
	v_cmp_lt_i32_e32 vcc, -1, v164
	s_and_b64 s[10:11], s[8:9], vcc
	v_min_u32_e32 v239, 0x7f, v164
	v_lshl_add_u32 v239, v239, 2, s3
	v_cndmask_b32_e64 v239, v242, v239, s[10:11]
	ds_read_b32 v239, v239
	v_add_u32_e32 v81, 0xfffffa31, v74
	v_cmp_lt_i32_e32 vcc, -1, v81
	v_cmp_gt_i32_e64 s[8:9], 9, v0
	s_and_b64 s[10:11], s[8:9], vcc
	v_min_u32_e32 v240, 0x7f, v81
	v_lshl_add_u32 v240, v240, 2, s3
	v_cndmask_b32_e64 v240, v242, v240, s[10:11]
	ds_read_b32 v240, v240
	v_add_u32_e32 v165, 0xfffff831, v74
	v_cmp_lt_i32_e32 vcc, -1, v165
	v_cmp_gt_i32_e64 s[8:9], 1, v0
	s_and_b64 s[10:11], s[8:9], vcc
	v_min_u32_e32 v241, 0x7f, v165
	v_lshl_add_u32 v241, v241, 2, s3
	v_cndmask_b32_e64 v241, v242, v241, s[10:11]
	ds_read_b32 v241, v241
	s_waitcnt lgkmcnt(0)
	v_add_f32_e32 v80, v50, v210
	v_add_f32_e32 v79, v34, v211
	v_add_f32_e32 v50, v51, v212
	v_add_f32_e32 v34, v35, v213
	v_add_f32_e32 v51, v52, v214
	v_add_f32_e32 v35, v36, v215
	v_add_f32_e32 v52, v53, v216
	v_add_f32_e32 v36, v37, v217
	v_add_f32_e32 v53, v54, v218
	v_add_f32_e32 v37, v38, v219
	v_add_f32_e32 v54, v55, v220
	v_add_f32_e32 v38, v39, v221
	v_add_f32_e32 v55, v56, v222
	v_add_f32_e32 v39, v40, v223
	v_add_f32_e32 v56, v57, v224
	v_add_f32_e32 v40, v41, v225
	v_add_f32_e32 v57, v58, v226
	v_add_f32_e32 v41, v42, v227
	v_add_f32_e32 v58, v59, v228
	v_add_f32_e32 v42, v43, v229
	v_add_f32_e32 v59, v60, v230
	v_add_f32_e32 v43, v44, v231
	v_add_f32_e32 v60, v61, v232
	v_add_f32_e32 v44, v45, v233
	v_add_f32_e32 v61, v62, v234
	v_add_f32_e32 v45, v46, v235
	v_add_f32_e32 v62, v63, v236
	v_add_f32_e32 v46, v47, v237
	v_add_f32_e32 v63, v64, v238
	v_add_f32_e32 v47, v48, v239
	v_add_f32_e32 v64, v65, v240
	v_add_f32_e32 v48, v49, v241
	v_max3_f32 v0, v191, v80, v79
	v_max_f32_e32 v65, v75, v75
	v_max3_f32 v0, v0, v50, v34
	v_max3_f32 v0, v0, v51, v35
	v_max3_f32 v0, v0, v52, v36
	v_max3_f32 v0, v0, v53, v37
	v_max3_f32 v0, v0, v54, v38
	v_max3_f32 v0, v0, v55, v39
	v_max3_f32 v0, v0, v56, v40
	v_max3_f32 v0, v0, v57, v41
	v_max3_f32 v0, v0, v58, v42
	v_max3_f32 v0, v0, v59, v43
	v_max3_f32 v0, v0, v60, v44
	v_max3_f32 v0, v0, v61, v45
	v_max3_f32 v0, v0, v62, v46
	v_max3_f32 v0, v0, v63, v47
	v_max3_f32 v0, v0, v64, v48
	ds_bpermute_b32 v49, v197, v0
	v_max_f32_e32 v0, v0, v0
	s_waitcnt lgkmcnt(0)
	v_max_f32_e32 v49, v49, v49
	v_max_f32_e32 v49, v0, v49
	v_max_f32_e32 v118, v65, v49
	v_sub_f32_e32 v35, v35, v118
	v_exp_f32_e32 v92, v35
	v_sub_f32_e32 v35, v52, v118
	v_exp_f32_e32 v125, v35
	v_sub_f32_e32 v35, v36, v118
	v_sub_f32_e32 v36, v53, v118
	v_exp_f32_e32 v136, v36
	v_sub_f32_e32 v36, v37, v118
	v_exp_f32_e32 v94, v36
	v_sub_f32_e32 v36, v54, v118
	v_exp_f32_e32 v138, v36
	v_sub_f32_e32 v36, v38, v118
	v_exp_f32_e32 v95, v36
	v_sub_f32_e32 v36, v55, v118
	v_exp_f32_e32 v141, v36
	v_sub_f32_e32 v36, v39, v118
	v_exp_f32_e32 v96, v36
	v_sub_f32_e32 v36, v56, v118
	v_sub_f32_e32 v0, v80, v118
	v_exp_f32_e32 v142, v36
	v_sub_f32_e32 v36, v40, v118
	v_sub_f32_e32 v65, v79, v118
	v_exp_f32_e32 v116, v0
	v_sub_f32_e32 v0, v50, v118
	v_exp_f32_e32 v97, v36
	v_sub_f32_e32 v36, v57, v118
	v_exp_f32_e32 v90, v65
	v_exp_f32_e32 v119, v0
	v_sub_f32_e32 v0, v34, v118
	v_exp_f32_e32 v120, v36
	v_sub_f32_e32 v36, v41, v118
	v_exp_f32_e32 v91, v0
	v_sub_f32_e32 v51, v51, v118
	v_exp_f32_e32 v114, v36
	v_sub_f32_e32 v36, v58, v118
	v_exp_f32_e32 v123, v51
	v_exp_f32_e32 v122, v36
	v_sub_f32_e32 v36, v42, v118
	v_exp_f32_e32 v93, v35
	v_exp_f32_e32 v115, v36
	v_sub_f32_e32 v36, v59, v118
	v_add_f32_e32 v34, v116, v90
	v_exp_f32_e32 v126, v36
	v_sub_f32_e32 v36, v43, v118
	v_add_f32_e32 v34, 0, v34
	v_add_f32_e32 v50, v119, v91
	v_exp_f32_e32 v117, v36
	v_sub_f32_e32 v36, v60, v118
	v_add_f32_e32 v34, v50, v34
	v_add_f32_e32 v35, v123, v92
	v_exp_f32_e32 v128, v36
	v_sub_f32_e32 v36, v44, v118
	v_add_f32_e32 v34, v35, v34
	v_add_f32_e32 v35, v125, v93
	v_exp_f32_e32 v121, v36
	v_sub_f32_e32 v36, v61, v118
	v_add_f32_e32 v34, v35, v34
	v_add_f32_e32 v35, v136, v94
	v_exp_f32_e32 v139, v36
	v_sub_f32_e32 v36, v45, v118
	v_add_f32_e32 v34, v35, v34
	v_add_f32_e32 v35, v138, v95
	v_exp_f32_e32 v124, v36
	v_sub_f32_e32 v36, v62, v118
	v_add_f32_e32 v34, v35, v34
	v_add_f32_e32 v35, v141, v96
	v_exp_f32_e32 v140, v36
	v_sub_f32_e32 v36, v46, v118
	v_add_f32_e32 v34, v35, v34
	v_add_f32_e32 v35, v142, v97
	v_exp_f32_e32 v127, v36
	v_sub_f32_e32 v36, v63, v118
	v_add_f32_e32 v34, v35, v34
	v_add_f32_e32 v35, v120, v114
	v_exp_f32_e32 v143, v36
	v_sub_f32_e32 v36, v47, v118
	v_add_f32_e32 v34, v35, v34
	v_add_f32_e32 v35, v122, v115
	v_exp_f32_e32 v129, v36
	v_sub_f32_e32 v36, v64, v118
	v_add_f32_e32 v34, v35, v34
	v_add_f32_e32 v35, v126, v117
	v_exp_f32_e32 v144, v36
	v_sub_f32_e32 v36, v48, v118
	v_add_f32_e32 v34, v35, v34
	v_add_f32_e32 v35, v128, v121
	v_exp_f32_e32 v137, v36
	v_add_f32_e32 v34, v35, v34
	v_add_f32_e32 v35, v139, v124
	v_add_f32_e32 v34, v35, v34
	v_add_f32_e32 v35, v140, v127
	v_add_f32_e32 v34, v35, v34
	v_add_f32_e32 v35, v143, v129
	v_add_f32_e32 v34, v35, v34
	v_add_f32_e32 v35, v144, v137
	v_add_f32_e32 v34, v35, v34
	v_sub_f32_e32 v0, v75, v118
	ds_bpermute_b32 v35, v197, v34
	v_exp_f32_e32 v0, v0
	v_cmp_gt_f32_e32 vcc, v49, v75
	s_cbranch_vccz .LBB0_1382
	v_mul_f32_e32 v32, v32, v0
	v_mul_f32_e32 v33, v33, v0
	v_mul_f32_e32 v30, v30, v0
	v_mul_f32_e32 v31, v31, v0
	v_mul_f32_e32 v28, v28, v0
	v_mul_f32_e32 v29, v29, v0
	v_mul_f32_e32 v26, v26, v0
	v_mul_f32_e32 v27, v27, v0
	v_mul_f32_e32 v24, v24, v0
	v_mul_f32_e32 v25, v25, v0
	v_mul_f32_e32 v22, v22, v0
	v_mul_f32_e32 v23, v23, v0
	v_mul_f32_e32 v20, v20, v0
	v_mul_f32_e32 v21, v21, v0
	v_mul_f32_e32 v18, v18, v0
	v_mul_f32_e32 v19, v19, v0
	v_mul_f32_e32 v16, v16, v0
	v_mul_f32_e32 v17, v17, v0
	v_mul_f32_e32 v14, v14, v0
	v_mul_f32_e32 v15, v15, v0
	v_mul_f32_e32 v12, v12, v0
	v_mul_f32_e32 v13, v13, v0
	v_mul_f32_e32 v10, v10, v0
	v_mul_f32_e32 v11, v11, v0
	v_mul_f32_e32 v8, v8, v0
	v_mul_f32_e32 v9, v9, v0
	v_mul_f32_e32 v6, v6, v0
	v_mul_f32_e32 v7, v7, v0
	v_mul_f32_e32 v4, v4, v0
	v_mul_f32_e32 v5, v5, v0
	v_mul_f32_e32 v2, v2, v0
	v_mul_f32_e32 v3, v3, v0

.LBB0_1416:
	v_cvt_pk_bf16_f32 v34, v116, v119
	v_cvt_pk_bf16_f32 v35, v123, v125
	v_cvt_pk_bf16_f32 v36, v136, v138
	v_cvt_pk_bf16_f32 v37, v141, v142
	s_mov_b32 s71, s67
	s_movk_i32 s8, 0x1000
	v_mfma_f32_32x32x16_bf16 v[18:33], v[66:69], v[34:37], v[18:33]
	v_cvt_pk_bf16_f32 v38, v114, v115
	v_cvt_pk_bf16_f32 v39, v117, v121
	v_cvt_pk_bf16_f32 v40, v124, v127
	v_cvt_pk_bf16_f32 v41, v129, v137
	v_lshl_add_u32 v200, v87, 2, 0
	v_add_u32_e32 v199, 0xa800, v200
	s_add_i32 s17, 0, 0x1c000
	v_mfma_f32_32x32x16_bf16 v[2:17], v[70:73], v[34:37], v[2:17]
	v_cvt_pk_bf16_f32 v34, v120, v122
	v_cvt_pk_bf16_f32 v35, v126, v128
	v_cvt_pk_bf16_f32 v36, v139, v140
	v_cvt_pk_bf16_f32 v37, v143, v144
	s_nop 1
	v_mfma_f32_32x32x16_bf16 v[18:33], v[74:77], v[34:37], v[18:33]
	v_mfma_f32_32x32x16_bf16 v[2:17], v[78:81], v[34:37], v[2:17]
	v_cvt_pk_bf16_f32 v34, v90, v91
	v_cvt_pk_bf16_f32 v35, v92, v93
	v_cvt_pk_bf16_f32 v36, v94, v95
	v_cvt_pk_bf16_f32 v37, v96, v97
	s_nop 1
	v_mfma_f32_32x32x16_bf16 v[18:33], v[62:65], v[34:37], v[18:33]
	v_mfma_f32_32x32x16_bf16 v[2:17], v[58:61], v[34:37], v[2:17]
	v_lshl_add_u64 v[34:35], v[82:83], 0, s[70:71]
	v_add_co_u32_e32 v36, vcc, s8, v34
	s_nop 1
	v_addc_co_u32_e32 v37, vcc, 0, v35, vcc
	v_mfma_f32_32x32x16_bf16 v[18:33], v[54:57], v[38:41], v[18:33]
	s_waitcnt vmcnt(0)
	v_lshlrev_b32_e32 v36, 16, v246
	v_mul_f32_e32 v36, 0xbfb8aa3b, v36
	v_exp_f32_e32 v36, v36
	v_mfma_f32_32x32x16_bf16 v[2:17], v[50:53], v[38:41], v[2:17]
	s_nop 6
	v_mul_f32_e64 v32, v0, v32
	v_mul_f32_e64 v33, v0, v33
	v_mul_f32_e64 v30, v0, v30
	v_mul_f32_e64 v31, v0, v31
	v_add_f32_e32 v36, 1.0, v36
	v_div_scale_f32 v37, s[8:9], v36, v36, 1.0
	v_rcp_f32_e32 v38, v37
	v_mul_f32_e32 v28, v0, v28
	v_mul_f32_e32 v29, v0, v29
	v_mul_f32_e32 v26, v0, v26
	v_mul_f32_e32 v27, v0, v27
	v_mul_f32_e32 v24, v0, v24
	v_mul_f32_e32 v25, v0, v25
	v_fma_f32 v39, -v37, v38, 1.0
	v_mul_f32_e32 v22, v0, v22
	v_mul_f32_e32 v23, v0, v23
	v_mul_f32_e32 v20, v0, v20
	v_mul_f32_e32 v21, v0, v21
	v_mul_f32_e32 v18, v0, v18
	v_mul_f32_e32 v19, v0, v19
	v_mul_f32_e32 v16, v0, v16
	v_mul_f32_e32 v17, v0, v17
	v_mul_f32_e32 v14, v0, v14
	v_mul_f32_e32 v15, v0, v15
	v_mul_f32_e32 v12, v0, v12
	v_mul_f32_e32 v13, v0, v13
	v_mul_f32_e32 v10, v0, v10
	v_mul_f32_e32 v11, v0, v11
	v_mul_f32_e32 v8, v0, v8
	v_mul_f32_e32 v9, v0, v9
	v_mul_f32_e32 v6, v0, v6
	v_mul_f32_e32 v7, v0, v7
	v_mul_f32_e32 v4, v0, v4
	v_mul_f32_e32 v5, v0, v5
	v_mul_f32_e32 v2, v0, v2
	v_mul_f32_e32 v3, v0, v3
	v_div_scale_f32 v0, vcc, 1.0, v36, 1.0
	v_fmac_f32_e32 v38, v39, v38
	v_mul_f32_e32 v39, v0, v38
	v_fma_f32 v40, -v37, v39, v0
	v_fmac_f32_e32 v39, v40, v38
	v_fma_f32 v0, -v37, v39, v0
	v_div_fmas_f32 v0, v0, v38, v39
	v_div_fixup_f32 v0, v0, v36, 1.0
	v_mul_f32_e32 v18, v18, v0
	v_mul_f32_e32 v19, v19, v0
	v_mul_f32_e32 v3, v3, v0
	v_mul_f32_e32 v5, v5, v0
	v_mul_f32_e32 v20, v20, v0
	v_mul_f32_e32 v4, v4, v0
	v_mul_f32_e32 v21, v21, v0
	v_mul_f32_e32 v22, v22, v0
	v_mul_f32_e32 v6, v6, v0
	v_mul_f32_e32 v23, v23, v0
	v_mul_f32_e32 v7, v7, v0
	v_mul_f32_e32 v24, v24, v0
	v_mul_f32_e32 v8, v8, v0
	v_mul_f32_e32 v25, v25, v0
	v_mul_f32_e32 v9, v9, v0
	v_mul_f32_e32 v26, v26, v0
	v_mul_f32_e32 v10, v10, v0
	v_mul_f32_e32 v27, v27, v0
	v_mul_f32_e32 v11, v11, v0
	v_mul_f32_e32 v28, v28, v0
	v_mul_f32_e32 v12, v12, v0
	v_mul_f32_e32 v29, v29, v0
	v_mul_f32_e32 v13, v13, v0
	v_mul_f32_e32 v30, v30, v0
	v_mul_f32_e32 v14, v14, v0
	ds_write2st64_b32 v200, v18, v19 offset0:168 offset1:176
	ds_write2st64_b32 v199, v3, v4 offset0:136 offset1:144
	ds_write2st64_b32 v200, v20, v21 offset0:184 offset1:192
	ds_write2st64_b32 v199, v5, v6 offset0:152 offset1:160
	ds_write2st64_b32 v200, v22, v23 offset0:200 offset1:208
	ds_write2st64_b32 v199, v7, v8 offset0:168 offset1:176
	ds_write2st64_b32 v200, v24, v25 offset0:216 offset1:224
	ds_write2st64_b32 v199, v9, v10 offset0:184 offset1:192
	ds_write2st64_b32 v200, v26, v27 offset0:232 offset1:240
	ds_write_b32 v200, v28 offset:63488
	ds_write2st64_b32 v199, v11, v12 offset0:200 offset1:208
	ds_write2st64_b32 v199, v29, v30 offset0:88 offset1:96
	ds_write2st64_b32 v199, v13, v14 offset0:216 offset1:224
	v_mul_f32_e32 v3, v31, v0
	v_mul_f32_e32 v5, v32, v0
	v_mul_f32_e32 v4, v15, v0
	ds_write2st64_b32 v199, v3, v5 offset0:104 offset1:112
	v_mul_f32_e32 v3, v16, v0
	v_mul_f32_e32 v2, v2, v0
	ds_write2st64_b32 v199, v4, v3 offset0:232 offset1:240
	v_mul_f32_e32 v3, v33, v0
	v_mul_f32_e32 v0, v17, v0
	ds_write_b32 v199, v0 offset:63488
	v_and_b32_e32 v0, 15, v84
	v_lshlrev_b32_e32 v8, 2, v0
	ds_write2st64_b32 v199, v3, v2 offset0:120 offset1:128
	v_ashrrev_i32_e32 v6, 4, v87
	s_movk_i32 s8, 0x204
	v_add_u32_e32 v2, -1, v8
	v_cmp_eq_u32_e32 vcc, 0, v0
	v_mul_lo_u32 v3, v6, s8
	v_add_u32_e32 v5, s17, v3
	v_cndmask_b32_e64 v7, v2, 0, vcc
	v_or_b32_e32 v2, 3, v8
	v_mov_b32_e32 v4, 0
	v_cmp_le_i32_e64 s[8:9], v7, v2
	v_mov_b32_e32 v9, 0
	s_waitcnt lgkmcnt(0)
	s_barrier
	s_and_saveexec_b64 s[10:11], s[8:9]
	s_cbranch_execz .LBB0_1426
	v_sub_u32_e32 v9, v8, v7
	v_add_u32_e32 v10, 4, v9
	v_cmp_lt_u32_e64 s[8:9], 1, v10
	s_mov_b64 s[14:15], -1
	v_mov_b32_e32 v9, 0
	s_and_saveexec_b64 s[12:13], s[8:9]
	s_cbranch_execz .LBB0_1421
	v_and_b32_e32 v11, -2, v10
	v_lshl_add_u32 v12, v7, 2, v5
	v_mov_b32_e32 v9, 0
	s_mov_b64 s[14:15], 0
	v_mov_b32_e32 v14, v11
	v_mov_b32_e32 v13, 0

.LBB0_1500:
	s_and_b64 vcc, exec, s[18:19]
	s_cbranch_vccz .LBB0_1502
	s_nop 6
	v_add_f32_e32 v80, v174, v64
	v_add_f32_e32 v81, v174, v65
	v_add_f32_e32 v78, v174, v62
	v_add_f32_e32 v79, v174, v63
	v_add_f32_e32 v76, v174, v60
	v_add_f32_e32 v77, v174, v61
	v_add_f32_e32 v74, v174, v58
	v_add_f32_e32 v75, v174, v59
	v_add_f32_e32 v72, v174, v56
	v_add_f32_e32 v73, v174, v57
	v_add_f32_e32 v70, v174, v54
	v_add_f32_e32 v71, v174, v55
	v_add_f32_e32 v68, v174, v52
	v_add_f32_e32 v69, v174, v53
	v_add_f32_e32 v66, v174, v50
	v_add_f32_e32 v67, v174, v51
	v_add_f32_e32 v96, v174, v48
	v_add_f32_e32 v97, v174, v49
	v_add_f32_e32 v94, v174, v46
	v_add_f32_e32 v95, v174, v47
	v_add_f32_e32 v92, v174, v44
	v_add_f32_e32 v93, v174, v45
	v_add_f32_e32 v90, v174, v42
	v_add_f32_e32 v91, v174, v43
	v_add_f32_e32 v88, v174, v40
	v_add_f32_e32 v89, v174, v41
	v_add_f32_e32 v86, v174, v38
	v_add_f32_e32 v87, v174, v39
	v_add_f32_e32 v84, v174, v36
	v_add_f32_e32 v85, v174, v37
	v_add_f32_e32 v82, v174, v34
	v_add_f32_e32 v83, v174, v35
.LBB0_1502:
	v_max3_f32 v34, v191, v66, v82
	s_nop 8
	v_max_f32_e32 v36, v177, v177
	v_max3_f32 v34, v34, v67, v83
	v_max3_f32 v34, v34, v68, v84
	v_max3_f32 v34, v34, v69, v85
	v_max3_f32 v34, v34, v70, v86
	v_max3_f32 v34, v34, v71, v87
	v_max3_f32 v34, v34, v72, v88
	v_max3_f32 v34, v34, v73, v89
	v_max3_f32 v34, v34, v74, v90
	v_max3_f32 v34, v34, v75, v91
	v_max3_f32 v34, v34, v76, v92
	v_max3_f32 v34, v34, v77, v93
	v_max3_f32 v34, v34, v78, v94
	v_max3_f32 v34, v34, v79, v95
	v_max3_f32 v34, v34, v80, v96
	v_max3_f32 v34, v34, v81, v97
	ds_bpermute_b32 v35, v197, v34
	v_max_f32_e32 v34, v34, v34
	s_waitcnt lgkmcnt(0)
	v_max_f32_e32 v35, v35, v35
	v_max_f32_e32 v174, v34, v35
	v_max_f32_e32 v35, v36, v174
	v_sub_f32_e32 v34, v66, v35
	v_sub_f32_e32 v36, v82, v35
	v_exp_f32_e32 v53, v34
	v_sub_f32_e32 v34, v67, v35
	v_exp_f32_e32 v36, v36
	v_exp_f32_e32 v55, v34
	v_sub_f32_e32 v34, v83, v35
	v_sub_f32_e32 v40, v68, v35
	v_exp_f32_e32 v39, v34
	v_exp_f32_e32 v58, v40
	v_sub_f32_e32 v40, v84, v35
	v_sub_f32_e32 v41, v69, v35
	v_exp_f32_e32 v40, v40
	v_exp_f32_e32 v60, v41
	v_sub_f32_e32 v41, v85, v35
	v_sub_f32_e32 v42, v70, v35
	v_sub_f32_e32 v44, v72, v35
	v_exp_f32_e32 v41, v41
	v_exp_f32_e32 v62, v42
	v_sub_f32_e32 v42, v86, v35
	v_sub_f32_e32 v43, v71, v35
	v_exp_f32_e32 v66, v44
	v_sub_f32_e32 v44, v88, v35
	v_add_f32_e32 v37, v53, v36
	v_exp_f32_e32 v42, v42
	v_exp_f32_e32 v64, v43
	v_sub_f32_e32 v43, v87, v35
	v_exp_f32_e32 v45, v44
	v_sub_f32_e32 v44, v73, v35
	v_add_f32_e32 v37, 0, v37
	v_add_f32_e32 v38, v55, v39
	v_exp_f32_e32 v43, v43
	v_exp_f32_e32 v68, v44
	v_sub_f32_e32 v44, v89, v35
	v_add_f32_e32 v37, v38, v37
	v_add_f32_e32 v38, v58, v40
	v_exp_f32_e32 v47, v44
	v_sub_f32_e32 v44, v74, v35
	v_add_f32_e32 v37, v38, v37
	v_add_f32_e32 v38, v60, v41
	v_exp_f32_e32 v52, v44
	v_sub_f32_e32 v44, v90, v35
	v_sub_f32_e32 v46, v75, v35
	v_add_f32_e32 v37, v38, v37
	v_add_f32_e32 v38, v62, v42
	v_exp_f32_e32 v44, v44
	v_exp_f32_e32 v56, v46
	v_sub_f32_e32 v46, v91, v35
	v_sub_f32_e32 v48, v76, v35
	v_add_f32_e32 v37, v38, v37
	v_add_f32_e32 v38, v64, v43
	v_exp_f32_e32 v46, v46
	v_exp_f32_e32 v59, v48
	v_sub_f32_e32 v48, v92, v35
	v_sub_f32_e32 v49, v77, v35
	v_add_f32_e32 v37, v38, v37
	v_add_f32_e32 v38, v66, v45
	v_exp_f32_e32 v48, v48
	v_exp_f32_e32 v61, v49
	v_sub_f32_e32 v49, v93, v35
	v_sub_f32_e32 v50, v78, v35
	v_add_f32_e32 v37, v38, v37
	v_add_f32_e32 v38, v68, v47
	v_exp_f32_e32 v49, v49
	v_exp_f32_e32 v63, v50
	v_sub_f32_e32 v50, v94, v35
	v_sub_f32_e32 v51, v79, v35
	v_add_f32_e32 v37, v38, v37
	v_add_f32_e32 v38, v52, v44
	v_exp_f32_e32 v50, v50
	v_exp_f32_e32 v65, v51
	v_sub_f32_e32 v51, v95, v35
	v_sub_f32_e32 v54, v80, v35
	v_add_f32_e32 v37, v38, v37
	v_add_f32_e32 v38, v56, v46
	v_exp_f32_e32 v51, v51
	v_exp_f32_e32 v67, v54
	v_sub_f32_e32 v54, v96, v35
	v_sub_f32_e32 v57, v81, v35
	v_add_f32_e32 v37, v38, v37
	v_add_f32_e32 v38, v59, v48
	v_exp_f32_e32 v54, v54
	v_exp_f32_e32 v69, v57
	v_sub_f32_e32 v57, v97, v35
	v_add_f32_e32 v37, v38, v37
	v_add_f32_e32 v38, v61, v49
	v_exp_f32_e32 v57, v57
	v_add_f32_e32 v37, v38, v37
	v_add_f32_e32 v38, v63, v50
	v_add_f32_e32 v37, v38, v37
	v_add_f32_e32 v38, v65, v51
	v_add_f32_e32 v37, v38, v37
	v_add_f32_e32 v38, v67, v54
	v_add_f32_e32 v37, v38, v37
	v_add_f32_e32 v38, v69, v57
	v_add_f32_e32 v37, v38, v37
	v_sub_f32_e32 v34, v177, v35
	ds_bpermute_b32 v38, v197, v37
	v_exp_f32_e32 v34, v34
	v_cmp_gt_f32_e32 vcc, v174, v177
	s_cbranch_vccz .LBB0_1504
	v_mul_f32_e32 v16, v16, v34
	v_mul_f32_e32 v17, v17, v34
	v_mul_f32_e32 v14, v14, v34
	v_mul_f32_e32 v15, v15, v34
	v_mul_f32_e32 v12, v12, v34
	v_mul_f32_e32 v13, v13, v34
	v_mul_f32_e32 v10, v10, v34
	v_mul_f32_e32 v11, v11, v34
	v_mul_f32_e32 v8, v8, v34
	v_mul_f32_e32 v9, v9, v34
	v_mul_f32_e32 v6, v6, v34
	v_mul_f32_e32 v7, v7, v34
	v_mul_f32_e32 v4, v4, v34
	v_mul_f32_e32 v5, v5, v34
	v_mul_f32_e32 v2, v2, v34
	v_mul_f32_e32 v3, v3, v34
	v_mul_f32_e32 v32, v32, v34
	v_mul_f32_e32 v33, v33, v34
	v_mul_f32_e32 v30, v30, v34
	v_mul_f32_e32 v31, v31, v34
	v_mul_f32_e32 v28, v28, v34
	v_mul_f32_e32 v29, v29, v34
	v_mul_f32_e32 v26, v26, v34
	v_mul_f32_e32 v27, v27, v34
	v_mul_f32_e32 v24, v24, v34
	v_mul_f32_e32 v25, v25, v34
	v_mul_f32_e32 v22, v22, v34
	v_mul_f32_e32 v23, v23, v34
	v_mul_f32_e32 v20, v20, v34
	v_mul_f32_e32 v21, v21, v34
	v_mul_f32_e32 v18, v18, v34
	v_mul_f32_e32 v19, v19, v34

.Lslc_farmask:
	s_nop 6
	v_add_f32_e32 v80, v174, v64
	v_add_f32_e32 v81, v174, v65
	v_add_f32_e32 v78, v174, v62
	v_add_f32_e32 v79, v174, v63
	v_add_f32_e32 v76, v174, v60
	v_add_f32_e32 v77, v174, v61
	v_add_f32_e32 v74, v174, v58
	v_add_f32_e32 v75, v174, v59
	v_add_f32_e32 v72, v174, v56
	v_add_f32_e32 v73, v174, v57
	v_add_f32_e32 v70, v174, v54
	v_add_f32_e32 v71, v174, v55
	v_add_f32_e32 v68, v174, v52
	v_add_f32_e32 v69, v174, v53
	v_add_f32_e32 v66, v174, v50
	v_add_f32_e32 v67, v174, v51
	v_add_f32_e32 v96, v174, v48
	v_add_f32_e32 v97, v174, v49
	v_add_f32_e32 v94, v174, v46
	v_add_f32_e32 v95, v174, v47
	v_add_f32_e32 v92, v174, v44
	v_add_f32_e32 v93, v174, v45
	v_add_f32_e32 v90, v174, v42
	v_add_f32_e32 v91, v174, v43
	v_add_f32_e32 v88, v174, v40
	v_add_f32_e32 v89, v174, v41
	v_add_f32_e32 v86, v174, v38
	v_add_f32_e32 v87, v174, v39
	v_add_f32_e32 v84, v174, v36
	v_add_f32_e32 v85, v174, v37
	v_add_f32_e32 v82, v174, v34
	v_add_f32_e32 v83, v174, v35
	s_mov_b64 vcc, s[8:9]
	v_cndmask_b32_e32 v66, v191, v66, vcc
	v_cndmask_b32_e32 v67, v191, v67, vcc
	v_cndmask_b32_e32 v68, v191, v68, vcc
	v_cndmask_b32_e32 v69, v191, v69, vcc
	v_cndmask_b32_e32 v70, v191, v70, vcc
	v_cndmask_b32_e32 v71, v191, v71, vcc
	v_cndmask_b32_e32 v72, v191, v72, vcc
	v_cndmask_b32_e32 v73, v191, v73, vcc
	v_cndmask_b32_e32 v74, v191, v74, vcc
	v_cndmask_b32_e32 v75, v191, v75, vcc
	v_cndmask_b32_e32 v76, v191, v76, vcc
	v_cndmask_b32_e32 v77, v191, v77, vcc
	v_cndmask_b32_e32 v78, v191, v78, vcc
	v_cndmask_b32_e32 v79, v191, v79, vcc
	v_cndmask_b32_e32 v80, v191, v80, vcc
	v_cndmask_b32_e32 v81, v191, v81, vcc
	v_cndmask_b32_e32 v82, v191, v82, vcc
	v_cndmask_b32_e32 v83, v191, v83, vcc
	v_cndmask_b32_e32 v84, v191, v84, vcc
	v_cndmask_b32_e32 v85, v191, v85, vcc
	v_cndmask_b32_e32 v86, v191, v86, vcc
	v_cndmask_b32_e32 v87, v191, v87, vcc
	v_cndmask_b32_e32 v88, v191, v88, vcc
	v_cndmask_b32_e32 v89, v191, v89, vcc
	v_cndmask_b32_e32 v90, v191, v90, vcc
	v_cndmask_b32_e32 v91, v191, v91, vcc
	v_cndmask_b32_e32 v92, v191, v92, vcc
	v_cndmask_b32_e32 v93, v191, v93, vcc
	v_cndmask_b32_e32 v94, v191, v94, vcc
	v_cndmask_b32_e32 v95, v191, v95, vcc
	v_cndmask_b32_e32 v96, v191, v96, vcc
	v_cndmask_b32_e32 v97, v191, v97, vcc
	s_branch .LBB0_1502

.LBB0_1539:
	global_load_ushort v53, v[136:137], off offset:2
	s_nop 1
	v_mov_b32_e32 v50, v9
	s_sub_i32 s8, 0x5e0, s7
	s_sub_i32 s16, 0x7ff, s7
	s_max_i32 s8, s8, -1
	s_ashr_i32 s9, s16, 6
	s_add_i32 s8, s8, 1
	s_add_i32 s10, s9, 1
	s_lshr_b32 s11, s8, 6
	s_lshl_b32 s8, -1, s10
	s_not_b32 s8, s8
	s_cmp_lg_u32 s9, 31
	v_mov_b32_e32 v51, v10
	s_cselect_b32 s10, s8, -1
	v_mov_b32_e32 v56, v12
	ds_read2st64_b32 v[34:35], v200 offset0:168 offset1:176
	ds_read2st64_b32 v[138:139], v199 offset0:120 offset1:128
	ds_read2st64_b32 v[36:37], v199 offset0:136 offset1:144
	ds_read2st64_b32 v[38:39], v200 offset0:184 offset1:192
	ds_read2st64_b32 v[40:41], v199 offset0:152 offset1:160
	ds_read2st64_b32 v[42:43], v200 offset0:200 offset1:208
	ds_read2st64_b32 v[44:45], v199 offset0:168 offset1:176
	ds_read2st64_b32 v[46:47], v200 offset0:216 offset1:224
	ds_read2st64_b32 v[48:49], v199 offset0:184 offset1:192
	ds_read2st64_b32 v[140:141], v200 offset0:232 offset1:240
	ds_read2st64_b32 v[54:55], v199 offset0:200 offset1:208
	v_mov_b32_e32 v57, v28
	ds_read2st64_b32 v[142:143], v199 offset0:88 offset1:96
	ds_read2st64_b32 v[144:145], v199 offset0:216 offset1:224
	ds_read2st64_b32 v[146:147], v199 offset0:104 offset1:112
	ds_read2st64_b32 v[148:149], v199 offset0:232 offset1:240
	ds_read_b32 v59, v200 offset:63488
	ds_read_b32 v219, v199 offset:63488
	s_lshl_b32 s11, -1, s11
	s_waitcnt lgkmcnt(7)
	v_mov_b32_e32 v61, v141
	s_waitcnt lgkmcnt(6)
	v_mov_b32_e32 v60, v54
	v_mov_b32_e32 v58, v55
	s_waitcnt vmcnt(0)
	v_lshlrev_b32_e32 v9, 16, v53
	v_mul_f32_e32 v9, 0xbfb8aa3b, v9
	v_exp_f32_e32 v9, v9
	s_nop 0
	v_add_f32_e32 v9, 1.0, v9
	v_div_scale_f32 v10, s[8:9], v9, v9, 1.0
	v_rcp_f32_e32 v12, v10
	v_div_scale_f32 v28, vcc, 1.0, v9, 1.0
	v_fma_f32 v53, -v10, v12, 1.0
	v_fmac_f32_e32 v12, v53, v12
	v_mul_f32_e32 v53, v28, v12
	v_fma_f32 v54, -v10, v53, v28
	v_fmac_f32_e32 v53, v54, v12
	v_fma_f32 v10, -v10, v53, v28
	v_div_fmas_f32 v10, v10, v12, v53
	v_div_fixup_f32 v9, v10, v9, 1.0
	v_div_scale_f32 v10, s[8:9], v52, v52, v9
	v_rcp_f32_e32 v12, v10
	v_div_scale_f32 v28, vcc, v9, v52, v9
	s_and_b32 s9, s11, s10
	v_fma_f32 v53, -v10, v12, 1.0
	v_fmac_f32_e32 v12, v53, v12
	v_mul_f32_e32 v53, v28, v12
	v_fma_f32 v54, -v10, v53, v28
	v_fmac_f32_e32 v53, v54, v12
	v_fma_f32 v10, -v10, v53, v28
	v_div_fmas_f32 v10, v10, v12, v53
	v_div_fixup_f32 v10, v10, v52, v9
	v_fmac_f32_e32 v140, v26, v10
	v_mov_b32_e32 v26, v11
	v_fma_f32 v9, v18, v10, v34
	v_fma_f32 v2, v2, v10, v139
	v_fmac_f32_e32 v35, v19, v10
	v_fma_f32 v150, v50, v10, v48
	v_fma_f32 v151, v51, v10, v49
	s_waitcnt lgkmcnt(1)
	v_fma_f32 v152, v56, v10, v58
	v_fma_f32 v153, v57, v10, v59
	v_fma_f32 v139, v29, v10, v142
	v_fma_f32 v141, v13, v10, v144
	v_fmac_f32_e32 v143, v30, v10
	v_fmac_f32_e32 v145, v14, v10
	v_fma_f32 v142, v31, v10, v146
	v_fma_f32 v144, v15, v10, v148
	v_fmac_f32_e32 v147, v32, v10
	v_fmac_f32_e32 v149, v16, v10
	v_fmac_f32_e32 v138, v33, v10
	s_waitcnt lgkmcnt(0)
	v_fmac_f32_e32 v219, v17, v10
	v_fma_f32 v154, v26, v10, v60
	v_fma_f32 v155, v27, v10, v61
	s_cmp_lg_u32 s9, 0
	v_fma_f32 v3, v3, v10, v36
	v_fma_f32 v12, v20, v10, v38
	v_fmac_f32_e32 v37, v4, v10
	v_fmac_f32_e32 v39, v21, v10
	v_fma_f32 v4, v5, v10, v40
	v_fma_f32 v5, v22, v10, v42
	v_fmac_f32_e32 v41, v6, v10
	v_fmac_f32_e32 v43, v23, v10
	v_fma_f32 v6, v7, v10, v44
	v_fma_f32 v7, v24, v10, v46
	v_fmac_f32_e32 v45, v8, v10
	v_fmac_f32_e32 v47, v25, v10
	ds_write2st64_b32 v200, v9, v35 offset0:168 offset1:176
	ds_write2st64_b32 v199, v3, v37 offset0:136 offset1:144
	ds_write2st64_b32 v200, v12, v39 offset0:184 offset1:192
	ds_write2st64_b32 v199, v4, v41 offset0:152 offset1:160
	ds_write2st64_b32 v200, v5, v43 offset0:200 offset1:208
	ds_write2st64_b32 v199, v6, v45 offset0:168 offset1:176
	ds_write2st64_b32 v200, v7, v47 offset0:216 offset1:224
	ds_write2st64_b32 v199, v150, v151 offset0:184 offset1:192
	ds_write_b32 v200, v153 offset:63488
	ds_write2st64_b32 v199, v139, v143 offset0:88 offset1:96
	ds_write2st64_b32 v199, v141, v145 offset0:216 offset1:224
	ds_write2st64_b32 v199, v142, v147 offset0:104 offset1:112
	ds_write2st64_b32 v199, v144, v149 offset0:232 offset1:240
	ds_write2st64_b32 v199, v138, v2 offset0:120 offset1:128
	ds_write2st64_b32 v200, v140, v155 offset0:232 offset1:240
	ds_write2st64_b32 v199, v154, v152 offset0:200 offset1:208
	ds_write_b32 v199, v219 offset:63488
	s_cbranch_scc0 .LBB0_1618
	s_add_u32 s8, s20, s46
	s_addc_u32 s13, s21, 0
	s_add_u32 s10, s8, 0x1700
	s_addc_u32 s11, s13, 0
	s_add_u32 s12, s8, 0x1600
	s_addc_u32 s13, s13, 0
	s_ff1_i32_b32 s8, s9
	s_add_i32 s14, s9, -1
	s_and_b32 s9, s14, s9
	s_mul_i32 s17, s8, 0x68000
	s_add_u32 s14, s12, s17
	s_addc_u32 s15, s13, 0
	global_load_dwordx4 v[2:5], v0, s[14:15]
	s_add_u32 s14, s10, s17
	s_addc_u32 s15, s11, 0
	global_load_dwordx4 v[6:9], v0, s[14:15]
	v_mov_b32_e32 v10, v1
	v_mov_b32_e32 v11, v1
	v_mov_b32_e32 v12, v1
	v_mov_b32_e32 v13, v1
	v_mov_b32_e32 v14, v1
	v_mov_b32_e32 v15, v1
	v_mov_b32_e32 v16, v1
	v_mov_b32_e32 v17, v1
	v_mov_b32_e32 v18, v1
	v_mov_b32_e32 v19, v1
	v_mov_b32_e32 v20, v1
	v_mov_b32_e32 v21, v1
	v_mov_b32_e32 v22, v1
	v_mov_b32_e32 v23, v1
	v_mov_b32_e32 v24, v1
	v_mov_b32_e32 v25, v1
	v_mov_b32_e32 v26, v1
	v_mov_b32_e32 v27, v1
	v_mov_b32_e32 v28, v1
	v_mov_b32_e32 v29, v1
	v_mov_b32_e32 v30, v1
	v_mov_b32_e32 v31, v1
	v_lshl_add_u64 v[156:157], s[10:11], 0, v[0:1]
	v_mov_b32_e32 v146, 0
	s_mov_b32 s17, 0
	s_addk_i32 s7, 0xf85e
	v_mov_b32_e32 v148, 0xf149f2ca
	v_mov_b32_e32 v158, 0
	v_mov_b32_e32 v159, v146
	v_mov_b32_e32 v160, 0
	v_mov_b32_e32 v161, v146
	v_mov_b32_e32 v162, 0
	v_mov_b32_e32 v163, v146
	v_mov_b32_e32 v164, 0
	v_mov_b32_e32 v165, v146
	v_mov_b32_e32 v166, 0
	v_mov_b32_e32 v167, v146
	v_mov_b32_e32 v168, 0
	v_mov_b32_e32 v169, v146
	v_mov_b32_e32 v170, 0
	v_mov_b32_e32 v171, v146
	v_mov_b32_e32 v172, 0
	v_mov_b32_e32 v173, v146
	v_mov_b32_e32 v174, 0
	v_mov_b32_e32 v175, v146
	v_mov_b32_e32 v176, 0
	v_mov_b32_e32 v177, v146
	v_mov_b32_e32 v178, 0
	v_mov_b32_e32 v179, v146
	v_mov_b32_e32 v180, 0
	v_mov_b32_e32 v181, v146
	v_mov_b32_e32 v182, 0
	v_mov_b32_e32 v183, v146
	v_mov_b32_e32 v184, 0
	v_mov_b32_e32 v185, v146
	v_mov_b32_e32 v186, 0
	v_mov_b32_e32 v187, v146
	v_mov_b32_e32 v188, 0
	v_mov_b32_e32 v189, v146
	s_mov_b32 s18, s8
	s_waitcnt vmcnt(1)
	ds_write_b128 v135, v[2:5]
	s_waitcnt vmcnt(0)
	ds_write_b128 v134, v[6:9] offset:9216
	v_mov_b32_e32 v2, v1
	v_mov_b32_e32 v3, v1
	v_mov_b32_e32 v4, v1
	v_mov_b32_e32 v5, v1
	v_mov_b32_e32 v6, v1
	v_mov_b32_e32 v7, v1
	v_mov_b32_e32 v8, v1
	v_mov_b32_e32 v9, v1
	v_lshl_add_u64 v[134:135], s[12:13], 0, v[0:1]
	v_mov_b32_e32 v0, v1
	v_mov_b64_e32 v[32:33], v[30:31]
	v_mov_b64_e32 v[30:31], v[28:29]
	v_mov_b64_e32 v[28:29], v[26:27]
	v_mov_b64_e32 v[26:27], v[24:25]
	v_mov_b64_e32 v[24:25], v[22:23]
	v_mov_b64_e32 v[22:23], v[20:21]
	v_mov_b64_e32 v[20:21], v[18:19]
	v_mov_b64_e32 v[18:19], v[16:17]
	v_mov_b64_e32 v[16:17], v[14:15]
	v_mov_b64_e32 v[14:15], v[12:13]
	v_mov_b64_e32 v[12:13], v[10:11]
	v_mov_b64_e32 v[10:11], v[8:9]
	v_mov_b64_e32 v[8:9], v[6:7]
	v_mov_b64_e32 v[6:7], v[4:5]
	v_mov_b64_e32 v[4:5], v[2:3]
	v_mov_b64_e32 v[2:3], v[0:1]
	s_waitcnt lgkmcnt(0)
	s_barrier

.LBB0_1579:
	s_and_b64 vcc, exec, s[8:9]
	s_cbranch_vccz .LBB0_1581
	s_nop 6
	v_add_f32_e32 v80, v0, v64
	v_add_f32_e32 v81, v0, v65
	v_add_f32_e32 v78, v0, v62
	v_add_f32_e32 v79, v0, v63
	v_add_f32_e32 v76, v0, v60
	v_add_f32_e32 v77, v0, v61
	v_add_f32_e32 v74, v0, v58
	v_add_f32_e32 v75, v0, v59
	v_add_f32_e32 v72, v0, v56
	v_add_f32_e32 v73, v0, v57
	v_add_f32_e32 v70, v0, v54
	v_add_f32_e32 v71, v0, v55
	v_add_f32_e32 v68, v0, v52
	v_add_f32_e32 v69, v0, v53
	v_add_f32_e32 v66, v0, v50
	v_add_f32_e32 v67, v0, v51
	v_add_f32_e32 v96, v0, v48
	v_add_f32_e32 v97, v0, v49
	v_add_f32_e32 v94, v0, v46
	v_add_f32_e32 v95, v0, v47
	v_add_f32_e32 v92, v0, v44
	v_add_f32_e32 v93, v0, v45
	v_add_f32_e32 v90, v0, v42
	v_add_f32_e32 v91, v0, v43
	v_add_f32_e32 v88, v0, v40
	v_add_f32_e32 v89, v0, v41
	v_add_f32_e32 v86, v0, v38
	v_add_f32_e32 v87, v0, v39
	v_add_f32_e32 v84, v0, v36
	v_add_f32_e32 v85, v0, v37
	v_add_f32_e32 v82, v0, v34
	v_add_f32_e32 v83, v0, v35
.LBB0_1581:
	v_max3_f32 v0, v191, v66, v82
	s_nop 8
	v_max_f32_e32 v35, v148, v148
	v_max3_f32 v0, v0, v67, v83
	v_max3_f32 v0, v0, v68, v84
	v_max3_f32 v0, v0, v69, v85
	v_max3_f32 v0, v0, v70, v86
	v_max3_f32 v0, v0, v71, v87
	v_max3_f32 v0, v0, v72, v88
	v_max3_f32 v0, v0, v73, v89
	v_max3_f32 v0, v0, v74, v90
	v_max3_f32 v0, v0, v75, v91
	v_max3_f32 v0, v0, v76, v92
	v_max3_f32 v0, v0, v77, v93
	v_max3_f32 v0, v0, v78, v94
	v_max3_f32 v0, v0, v79, v95
	v_max3_f32 v0, v0, v80, v96
	v_max3_f32 v0, v0, v81, v97
	ds_bpermute_b32 v34, v197, v0
	v_max_f32_e32 v0, v0, v0
	s_waitcnt lgkmcnt(0)
	v_max_f32_e32 v34, v34, v34
	v_max_f32_e32 v221, v0, v34
	v_max_f32_e32 v34, v35, v221
	v_sub_f32_e32 v0, v66, v34
	v_sub_f32_e32 v35, v82, v34
	v_exp_f32_e32 v52, v0
	v_sub_f32_e32 v0, v67, v34
	v_exp_f32_e32 v35, v35
	v_exp_f32_e32 v54, v0
	v_sub_f32_e32 v0, v83, v34
	v_sub_f32_e32 v39, v68, v34
	v_exp_f32_e32 v38, v0
	v_exp_f32_e32 v57, v39
	v_sub_f32_e32 v39, v84, v34
	v_sub_f32_e32 v40, v69, v34
	v_exp_f32_e32 v39, v39
	v_exp_f32_e32 v59, v40
	v_sub_f32_e32 v40, v85, v34
	v_sub_f32_e32 v41, v70, v34
	v_sub_f32_e32 v43, v72, v34
	v_exp_f32_e32 v40, v40
	v_exp_f32_e32 v61, v41
	v_sub_f32_e32 v41, v86, v34
	v_sub_f32_e32 v42, v71, v34
	v_exp_f32_e32 v65, v43
	v_sub_f32_e32 v43, v88, v34
	v_add_f32_e32 v36, v52, v35
	v_exp_f32_e32 v41, v41
	v_exp_f32_e32 v63, v42
	v_sub_f32_e32 v42, v87, v34
	v_exp_f32_e32 v44, v43
	v_sub_f32_e32 v43, v73, v34
	v_add_f32_e32 v36, 0, v36
	v_add_f32_e32 v37, v54, v38
	v_exp_f32_e32 v42, v42
	v_exp_f32_e32 v67, v43
	v_sub_f32_e32 v43, v89, v34
	v_add_f32_e32 v36, v37, v36
	v_add_f32_e32 v37, v57, v39
	v_exp_f32_e32 v46, v43
	v_sub_f32_e32 v43, v74, v34
	v_add_f32_e32 v36, v37, v36
	v_add_f32_e32 v37, v59, v40
	v_exp_f32_e32 v51, v43
	v_sub_f32_e32 v43, v90, v34
	v_sub_f32_e32 v45, v75, v34
	v_add_f32_e32 v36, v37, v36
	v_add_f32_e32 v37, v61, v41
	v_exp_f32_e32 v43, v43
	v_exp_f32_e32 v55, v45
	v_sub_f32_e32 v45, v91, v34
	v_sub_f32_e32 v47, v76, v34
	v_add_f32_e32 v36, v37, v36
	v_add_f32_e32 v37, v63, v42
	v_exp_f32_e32 v45, v45
	v_exp_f32_e32 v58, v47
	v_sub_f32_e32 v47, v92, v34
	v_sub_f32_e32 v48, v77, v34
	v_add_f32_e32 v36, v37, v36
	v_add_f32_e32 v37, v65, v44
	v_exp_f32_e32 v47, v47
	v_exp_f32_e32 v60, v48
	v_sub_f32_e32 v48, v93, v34
	v_sub_f32_e32 v49, v78, v34
	v_add_f32_e32 v36, v37, v36
	v_add_f32_e32 v37, v67, v46
	v_exp_f32_e32 v48, v48
	v_exp_f32_e32 v62, v49
	v_sub_f32_e32 v49, v94, v34
	v_sub_f32_e32 v50, v79, v34
	v_add_f32_e32 v36, v37, v36
	v_add_f32_e32 v37, v51, v43
	v_exp_f32_e32 v49, v49
	v_exp_f32_e32 v64, v50
	v_sub_f32_e32 v50, v95, v34
	v_sub_f32_e32 v53, v80, v34
	v_add_f32_e32 v36, v37, v36
	v_add_f32_e32 v37, v55, v45
	v_exp_f32_e32 v50, v50
	v_exp_f32_e32 v66, v53
	v_sub_f32_e32 v53, v96, v34
	v_sub_f32_e32 v56, v81, v34
	v_add_f32_e32 v36, v37, v36
	v_add_f32_e32 v37, v58, v47
	v_exp_f32_e32 v53, v53
	v_exp_f32_e32 v68, v56
	v_sub_f32_e32 v56, v97, v34
	v_add_f32_e32 v36, v37, v36
	v_add_f32_e32 v37, v60, v48
	v_exp_f32_e32 v56, v56
	v_add_f32_e32 v36, v37, v36
	v_add_f32_e32 v37, v62, v49
	v_add_f32_e32 v36, v37, v36
	v_add_f32_e32 v37, v64, v50
	v_add_f32_e32 v36, v37, v36
	v_add_f32_e32 v37, v66, v53
	v_add_f32_e32 v36, v37, v36
	v_add_f32_e32 v37, v68, v56
	v_add_f32_e32 v36, v37, v36
	v_sub_f32_e32 v0, v148, v34
	ds_bpermute_b32 v37, v197, v36
	v_exp_f32_e32 v0, v0
	v_cmp_gt_f32_e32 vcc, v221, v148
	s_cbranch_vccz .LBB0_1583
	v_mul_f32_e32 v32, v32, v0
	v_mul_f32_e32 v33, v33, v0
	v_mul_f32_e32 v30, v30, v0
	v_mul_f32_e32 v31, v31, v0
	v_mul_f32_e32 v28, v28, v0
	v_mul_f32_e32 v29, v29, v0
	v_mul_f32_e32 v26, v26, v0
	v_mul_f32_e32 v27, v27, v0
	v_mul_f32_e32 v24, v24, v0
	v_mul_f32_e32 v25, v25, v0
	v_mul_f32_e32 v22, v22, v0
	v_mul_f32_e32 v23, v23, v0
	v_mul_f32_e32 v20, v20, v0
	v_mul_f32_e32 v21, v21, v0
	v_mul_f32_e32 v18, v18, v0
	v_mul_f32_e32 v19, v19, v0
	v_mul_f32_e32 v16, v16, v0
	v_mul_f32_e32 v17, v17, v0
	v_mul_f32_e32 v14, v14, v0
	v_mul_f32_e32 v15, v15, v0
	v_mul_f32_e32 v12, v12, v0
	v_mul_f32_e32 v13, v13, v0
	v_mul_f32_e32 v10, v10, v0
	v_mul_f32_e32 v11, v11, v0
	v_mul_f32_e32 v8, v8, v0
	v_mul_f32_e32 v9, v9, v0
	v_mul_f32_e32 v6, v6, v0
	v_mul_f32_e32 v7, v7, v0
	v_mul_f32_e32 v4, v4, v0
	v_mul_f32_e32 v5, v5, v0
	v_mul_f32_e32 v2, v2, v0
	v_mul_f32_e32 v3, v3, v0

.LBB0_2618:
	v_div_scale_f32 v0, s[16:17], v206, v206, 1.0
	v_rcp_f32_e32 v2, v0
	v_div_scale_f32 v3, vcc, 1.0, v206, 1.0
	v_ashrrev_i32_e32 v185, 31, v184
	v_fma_f32 v4, -v0, v2, 1.0
	v_fmac_f32_e32 v2, v4, v2
	v_mul_f32_e32 v4, v3, v2
	v_fma_f32 v5, -v0, v4, v3
	v_fmac_f32_e32 v4, v5, v2
	v_fma_f32 v0, -v0, v4, v3
	v_div_fmas_f32 v0, v0, v2, v4
	v_div_fixup_f32 v0, v0, v206, 1.0
	v_mul_f32_e32 v14, v66, v0
	v_mul_f32_e32 v15, v67, v0
	v_lshlrev_b64 v[66:67], 12, v[184:185]
	v_lshl_add_u64 v[66:67], s[50:51], 0, v[66:67]
	s_lshl_b32 s6, s22, 8
	v_mul_f32_e32 v2, v78, v0
	v_mul_f32_e32 v3, v79, v0
	v_mul_f32_e32 v4, v76, v0
	v_mul_f32_e32 v5, v77, v0
	v_mul_f32_e32 v50, v50, v0
	v_mul_f32_e32 v51, v51, v0
	v_mul_f32_e32 v48, v48, v0
	v_mul_f32_e32 v49, v49, v0
	v_lshl_add_u64 v[66:67], v[66:67], 0, s[6:7]
	v_ashrrev_i32_e32 v187, 31, v186
	v_mul_f32_e32 v54, v54, v0
	v_mul_f32_e32 v55, v55, v0
	v_mul_f32_e32 v52, v52, v0
	v_mul_f32_e32 v53, v53, v0
	v_lshl_add_u64 v[66:67], v[186:187], 1, v[66:67]
	v_cvt_pk_bf16_f32 v4, v4, v5
	v_cvt_pk_bf16_f32 v5, v2, v3
	v_cvt_pk_bf16_f32 v2, v48, v49
	v_cvt_pk_bf16_f32 v3, v50, v51
	v_mul_f32_e32 v58, v58, v0
	v_mul_f32_e32 v59, v59, v0
	v_mul_f32_e32 v56, v56, v0
	v_mul_f32_e32 v57, v57, v0
	global_store_dwordx2 v[66:67], v[2:3], off offset:64
	v_cvt_pk_bf16_f32 v2, v52, v53
	v_cvt_pk_bf16_f32 v3, v54, v55
	v_mul_f32_e32 v62, v62, v0
	v_mul_f32_e32 v63, v63, v0
	v_mul_f32_e32 v60, v60, v0
	v_mul_f32_e32 v61, v61, v0
	global_store_dwordx2 v[66:67], v[2:3], off offset:80
	v_cvt_pk_bf16_f32 v2, v56, v57
	v_cvt_pk_bf16_f32 v3, v58, v59
	v_mul_f32_e32 v34, v34, v0
	v_mul_f32_e32 v35, v35, v0
	v_mul_f32_e32 v32, v32, v0
	v_mul_f32_e32 v33, v33, v0
	global_store_dwordx2 v[66:67], v[2:3], off offset:96
	v_cvt_pk_bf16_f32 v2, v60, v61
	v_cvt_pk_bf16_f32 v3, v62, v63
	v_mul_f32_e32 v38, v38, v0
	v_mul_f32_e32 v39, v39, v0
	v_mul_f32_e32 v36, v36, v0
	v_mul_f32_e32 v37, v37, v0
	global_store_dwordx2 v[66:67], v[2:3], off offset:112
	v_cvt_pk_bf16_f32 v2, v32, v33
	v_cvt_pk_bf16_f32 v3, v34, v35
	v_mul_f32_e32 v42, v42, v0
	v_mul_f32_e32 v43, v43, v0
	v_mul_f32_e32 v40, v40, v0
	v_mul_f32_e32 v41, v41, v0
	global_store_dwordx2 v[66:67], v[2:3], off offset:128
	v_cvt_pk_bf16_f32 v2, v36, v37
	v_cvt_pk_bf16_f32 v3, v38, v39
	v_mul_f32_e32 v46, v46, v0
	v_mul_f32_e32 v47, v47, v0
	v_mul_f32_e32 v44, v44, v0
	v_mul_f32_e32 v45, v45, v0
	global_store_dwordx2 v[66:67], v[2:3], off offset:144
	v_cvt_pk_bf16_f32 v2, v40, v41
	v_cvt_pk_bf16_f32 v3, v42, v43
	v_mul_f32_e32 v18, v18, v0
	v_mul_f32_e32 v19, v19, v0
	v_mul_f32_e32 v16, v16, v0
	v_mul_f32_e32 v17, v17, v0
	global_store_dwordx2 v[66:67], v[2:3], off offset:160
	v_cvt_pk_bf16_f32 v2, v44, v45
	v_cvt_pk_bf16_f32 v3, v46, v47
	v_mul_f32_e32 v22, v22, v0
	v_mul_f32_e32 v23, v23, v0
	v_mul_f32_e32 v20, v20, v0
	v_mul_f32_e32 v21, v21, v0
	global_store_dwordx2 v[66:67], v[2:3], off offset:176
	v_cvt_pk_bf16_f32 v2, v16, v17
	v_cvt_pk_bf16_f32 v3, v18, v19
	v_mul_f32_e32 v26, v26, v0
	v_mul_f32_e32 v27, v27, v0
	v_mul_f32_e32 v24, v24, v0
	v_mul_f32_e32 v25, v25, v0
	global_store_dwordx2 v[66:67], v[2:3], off offset:192
	v_cvt_pk_bf16_f32 v2, v20, v21
	v_cvt_pk_bf16_f32 v3, v22, v23
	v_mul_f32_e32 v6, v74, v0
	v_mul_f32_e32 v7, v75, v0
	v_mul_f32_e32 v8, v72, v0
	v_mul_f32_e32 v9, v73, v0
	v_mul_f32_e32 v10, v70, v0
	v_mul_f32_e32 v11, v71, v0
	v_mul_f32_e32 v12, v68, v0
	v_mul_f32_e32 v13, v69, v0
	v_mul_f32_e32 v64, v64, v0
	v_mul_f32_e32 v65, v65, v0
	v_mul_f32_e32 v30, v30, v0
	v_mul_f32_e32 v31, v31, v0
	v_mul_f32_e32 v28, v28, v0
	v_mul_f32_e32 v29, v29, v0
	global_store_dwordx2 v[66:67], v[2:3], off offset:208
	v_cvt_pk_bf16_f32 v2, v24, v25
	v_cvt_pk_bf16_f32 v3, v26, v27
	v_cvt_pk_bf16_f32 v64, v64, v65
	v_cvt_pk_bf16_f32 v65, v14, v15
	v_cvt_pk_bf16_f32 v12, v12, v13
	v_cvt_pk_bf16_f32 v13, v10, v11
	v_cvt_pk_bf16_f32 v8, v8, v9
	v_cvt_pk_bf16_f32 v9, v6, v7
	global_store_dwordx2 v[66:67], v[2:3], off offset:224
	v_cvt_pk_bf16_f32 v2, v28, v29
	v_cvt_pk_bf16_f32 v3, v30, v31
	s_mov_b64 s[16:17], 0
	global_store_dwordx2 v[66:67], v[64:65], off
	global_store_dwordx2 v[66:67], v[12:13], off offset:16
	global_store_dwordx2 v[66:67], v[8:9], off offset:32
	global_store_dwordx2 v[66:67], v[4:5], off offset:48
	global_store_dwordx2 v[66:67], v[2:3], off offset:240

.LBB0_2633:
	v_max3_f32 v0, v193, v96, v80
	v_max_f32_e32 v208, v207, v207
	v_max3_f32 v0, v0, v97, v81
	v_max3_f32 v0, v0, v98, v82
	v_max3_f32 v0, v0, v99, v83
	v_max3_f32 v0, v0, v100, v84
	v_max3_f32 v0, v0, v101, v85
	v_max3_f32 v0, v0, v102, v86
	v_max3_f32 v0, v0, v103, v87
	v_max3_f32 v0, v0, v104, v88
	v_max3_f32 v0, v0, v105, v89
	v_max3_f32 v0, v0, v106, v90
	v_max3_f32 v0, v0, v107, v91
	v_max3_f32 v0, v0, v108, v92
	v_max3_f32 v0, v0, v109, v93
	v_max3_f32 v0, v0, v110, v94
	v_max3_f32 v0, v0, v111, v95
	ds_bpermute_b32 v15, v205, v0
	v_max_f32_e32 v0, v0, v0
	s_waitcnt lgkmcnt(0)
	v_max_f32_e32 v15, v15, v15
	v_max_f32_e32 v216, v0, v15
	v_max_f32_e32 v15, v208, v216
	v_sub_f32_e32 v0, v96, v15
	v_sub_f32_e32 v80, v80, v15
	v_exp_f32_e32 v208, v0
	v_sub_f32_e32 v0, v97, v15
	v_exp_f32_e32 v80, v80
	v_exp_f32_e32 v209, v0
	v_sub_f32_e32 v0, v81, v15
	v_exp_f32_e32 v81, v0
	v_sub_f32_e32 v98, v98, v15
	v_sub_f32_e32 v82, v82, v15
	v_exp_f32_e32 v210, v98
	v_exp_f32_e32 v82, v82
	v_add_f32_e32 v96, v208, v80
	v_sub_f32_e32 v98, v99, v15
	v_sub_f32_e32 v83, v83, v15
	v_add_f32_e32 v96, 0, v96
	v_add_f32_e32 v97, v209, v81
	v_exp_f32_e32 v211, v98
	v_exp_f32_e32 v83, v83
	v_add_f32_e32 v96, v97, v96
	v_add_f32_e32 v97, v210, v82
	v_add_f32_e32 v98, v97, v96
	v_sub_f32_e32 v96, v100, v15
	v_sub_f32_e32 v84, v84, v15
	v_exp_f32_e32 v212, v96
	v_exp_f32_e32 v96, v84
	v_sub_f32_e32 v84, v101, v15
	v_add_f32_e32 v99, v211, v83
	v_exp_f32_e32 v213, v84
	v_sub_f32_e32 v84, v85, v15
	v_exp_f32_e32 v97, v84
	v_add_f32_e32 v84, v99, v98
	v_sub_f32_e32 v98, v102, v15
	v_sub_f32_e32 v86, v86, v15
	v_exp_f32_e32 v214, v98
	v_exp_f32_e32 v98, v86
	v_add_f32_e32 v85, v212, v96
	v_add_f32_e32 v84, v85, v84
	v_add_f32_e32 v85, v213, v97
	v_sub_f32_e32 v86, v103, v15
	v_exp_f32_e32 v215, v86
	v_sub_f32_e32 v86, v87, v15
	v_add_f32_e32 v84, v85, v84
	v_add_f32_e32 v85, v214, v98
	v_exp_f32_e32 v99, v86
	v_add_f32_e32 v86, v85, v84
	v_sub_f32_e32 v84, v104, v15
	v_exp_f32_e32 v100, v84
	v_sub_f32_e32 v84, v88, v15
	v_exp_f32_e32 v84, v84
	v_add_f32_e32 v87, v215, v99
	v_sub_f32_e32 v85, v105, v15
	v_add_f32_e32 v86, v87, v86
	v_add_f32_e32 v87, v100, v84
	v_exp_f32_e32 v101, v85
	v_sub_f32_e32 v85, v89, v15
	v_add_f32_e32 v88, v87, v86
	v_sub_f32_e32 v86, v106, v15
	v_exp_f32_e32 v85, v85
	v_exp_f32_e32 v102, v86
	v_sub_f32_e32 v86, v90, v15
	v_exp_f32_e32 v86, v86
	v_add_f32_e32 v89, v101, v85
	v_sub_f32_e32 v87, v107, v15
	v_add_f32_e32 v88, v89, v88
	v_add_f32_e32 v89, v102, v86
	v_exp_f32_e32 v103, v87
	v_sub_f32_e32 v87, v91, v15
	v_add_f32_e32 v90, v89, v88
	v_sub_f32_e32 v88, v108, v15
	v_exp_f32_e32 v87, v87
	v_exp_f32_e32 v104, v88
	v_sub_f32_e32 v88, v92, v15
	v_exp_f32_e32 v88, v88
	v_add_f32_e32 v91, v103, v87
	v_sub_f32_e32 v89, v109, v15
	v_add_f32_e32 v90, v91, v90
	v_add_f32_e32 v91, v104, v88
	v_exp_f32_e32 v92, v89
	v_sub_f32_e32 v89, v93, v15
	v_add_f32_e32 v105, v91, v90
	v_sub_f32_e32 v90, v110, v15
	v_exp_f32_e32 v89, v89
	v_exp_f32_e32 v93, v90
	v_sub_f32_e32 v90, v94, v15
	v_sub_f32_e32 v91, v111, v15
	v_exp_f32_e32 v90, v90
	v_exp_f32_e32 v94, v91
	v_sub_f32_e32 v91, v95, v15
	v_exp_f32_e32 v91, v91
	v_add_f32_e32 v106, v92, v89
	v_add_f32_e32 v95, v106, v105
	v_add_f32_e32 v105, v93, v90
	v_add_f32_e32 v95, v105, v95
	v_add_f32_e32 v105, v94, v91
	v_add_f32_e32 v95, v105, v95
	v_sub_f32_e32 v0, v207, v15
	ds_bpermute_b32 v105, v205, v95
	v_exp_f32_e32 v0, v0
	v_cmp_gt_f32_e32 vcc, v216, v207
	s_cbranch_vccz .LBB0_2635
	v_mul_f32_e32 v78, v78, v0
	v_mul_f32_e32 v79, v79, v0
	v_mul_f32_e32 v76, v76, v0
	v_mul_f32_e32 v77, v77, v0
	v_mul_f32_e32 v74, v74, v0
	v_mul_f32_e32 v75, v75, v0
	v_mul_f32_e32 v72, v72, v0
	v_mul_f32_e32 v73, v73, v0
	v_mul_f32_e32 v70, v70, v0
	v_mul_f32_e32 v71, v71, v0
	v_mul_f32_e32 v68, v68, v0
	v_mul_f32_e32 v69, v69, v0
	v_mul_f32_e32 v66, v66, v0
	v_mul_f32_e32 v67, v67, v0
	v_mul_f32_e32 v64, v64, v0
	v_mul_f32_e32 v65, v65, v0
	v_mul_f32_e32 v62, v62, v0
	v_mul_f32_e32 v63, v63, v0
	v_mul_f32_e32 v60, v60, v0
	v_mul_f32_e32 v61, v61, v0
	v_mul_f32_e32 v58, v58, v0
	v_mul_f32_e32 v59, v59, v0
	v_mul_f32_e32 v56, v56, v0
	v_mul_f32_e32 v57, v57, v0
	v_mul_f32_e32 v54, v54, v0
	v_mul_f32_e32 v55, v55, v0
	v_mul_f32_e32 v52, v52, v0
	v_mul_f32_e32 v53, v53, v0
	v_mul_f32_e32 v50, v50, v0
	v_mul_f32_e32 v51, v51, v0
	v_mul_f32_e32 v48, v48, v0
	v_mul_f32_e32 v49, v49, v0
	v_mul_f32_e32 v46, v46, v0
	v_mul_f32_e32 v47, v47, v0
	v_mul_f32_e32 v44, v44, v0
	v_mul_f32_e32 v45, v45, v0
	v_mul_f32_e32 v42, v42, v0
	v_mul_f32_e32 v43, v43, v0
	v_mul_f32_e32 v40, v40, v0
	v_mul_f32_e32 v41, v41, v0
	v_mul_f32_e32 v38, v38, v0
	v_mul_f32_e32 v39, v39, v0
	v_mul_f32_e32 v36, v36, v0
	v_mul_f32_e32 v37, v37, v0
	v_mul_f32_e32 v34, v34, v0
	v_mul_f32_e32 v35, v35, v0
	v_mul_f32_e32 v32, v32, v0
	v_mul_f32_e32 v33, v33, v0
	v_mul_f32_e32 v30, v30, v0
	v_mul_f32_e32 v31, v31, v0
	v_mul_f32_e32 v28, v28, v0
	v_mul_f32_e32 v29, v29, v0
	v_mul_f32_e32 v26, v26, v0
	v_mul_f32_e32 v27, v27, v0
	v_mul_f32_e32 v24, v24, v0
	v_mul_f32_e32 v25, v25, v0
	v_mul_f32_e32 v22, v22, v0
	v_mul_f32_e32 v23, v23, v0
	v_mul_f32_e32 v20, v20, v0
	v_mul_f32_e32 v21, v21, v0
	v_mul_f32_e32 v18, v18, v0
	v_mul_f32_e32 v19, v19, v0
	v_mul_f32_e32 v16, v16, v0
	v_mul_f32_e32 v17, v17, v0
